# next-layer weight conversion (inside the mixer phase): the six transpose items whose 32 loads were issued two at a time behind vmcnt(1)/(0) now issue all 32 loads, wait once, then do the LDS writes
# speedup vs baseline: 1.0063x; 1.0063x over previous
; #define LAS __attribute__((address_space(3)))
; template <bool F16 = false> __device__ __forceinline__ void tr_item(const float* W, int N, bf16* WT, int ldk, int koff, int k0, int n0, int drow0, LAS float* scr, int lane) {
; #pragma unroll 16
;     for (int i = 0; i < 32; ++i) { const int kk = 2 * i + (lane >> 5); scr[kk * 33 + (lane & 31)] = W[(size_t)(k0 + kk) * N + n0 + (lane & 31)]; }
;     asm volatile("s_waitcnt lgkmcnt(0)" ::: "memory");
; __device__ __forceinline__ void convert_layer(const Args& a, int l, LAS unsigned char* lds, int gw, int NGW, int lane, int wave, bool gates = true) {
;     ...
;         tr_item(w_pe, DM, (bf16*)(ws + WS_WE), 256, 0, 64 * (r >> 5), 32 * (r & 31), 32 * (r & 31), scr, lane);
.LBB0_610:
	s_cmpk_gt_i32 s39, 0x11ff
	s_mov_b64 s[18:19], -1
	s_cbranch_scc0 .LBB0_628
	s_cmpk_gt_u32 s39, 0x13ff
	s_cbranch_scc0 .LBB0_625
	s_cmpk_gt_u32 s39, 0x15ff
	s_cbranch_scc0 .LBB0_622
	s_cmpk_gt_u32 s39, 0x17ff
	s_cbranch_scc0 .LBB0_619
	s_and_b32 s10, s31, 0x3e0
	s_cmpk_gt_u32 s39, 0x19ff
	v_or_b32_e32 v102, s10, v57
	v_or_b32_e32 v101, s10, v59
	v_or_b32_e32 v100, s10, v60
	v_or_b32_e32 v99, s10, v61
	s_cbranch_scc0 .LBB0_616
	s_and_b32 s11, s37, 0x7fffffc0
	v_or_b32_e32 v52, s11, v1
	v_or_b32_e32 v53, s11, v0
	v_lshlrev_b32_e32 v64, 10, v52
	v_lshlrev_b32_e32 v53, 10, v53
	v_or_b32_e32 v52, s10, v55
	v_or_b32_e32 v104, v52, v64
	v_or_b32_e32 v64, v52, v53
	v_lshl_add_u64 v[106:107], v[64:65], 2, s[12:13]
	v_mov_b32_e32 v105, v65
	v_lshl_add_u64 v[104:105], v[104:105], 2, s[12:13]
	global_load_dword v156, v[106:107], off
	global_load_dword v157, v[104:105], off
	v_mov_b32_e32 v105, v65
	v_readlane_b32 s18, v254, 58
	v_readlane_b32 s19, v254, 59
	s_lshl_b32 s18, s11, 1
	v_or_b32_e32 v64, s11, v22
	v_or_b32_e32 v53, s11, v23
	v_lshlrev_b32_e32 v64, 10, v64
	v_lshlrev_b32_e32 v53, 10, v53
	v_or_b32_e32 v64, v52, v64
	v_or_b32_e32 v104, v52, v53
	v_lshl_add_u64 v[106:107], v[64:65], 2, s[12:13]
	v_lshl_add_u64 v[104:105], v[104:105], 2, s[12:13]
	global_load_dword v158, v[106:107], off
	global_load_dword v159, v[104:105], off
	v_mov_b32_e32 v105, v65
	v_or_b32_e32 v64, s11, v24
	v_or_b32_e32 v53, s11, v25
	v_lshlrev_b32_e32 v64, 10, v64
	v_lshlrev_b32_e32 v53, 10, v53
	v_or_b32_e32 v64, v52, v64
	v_or_b32_e32 v104, v52, v53
	v_lshl_add_u64 v[106:107], v[64:65], 2, s[12:13]
	v_lshl_add_u64 v[104:105], v[104:105], 2, s[12:13]
	global_load_dword v160, v[106:107], off
	global_load_dword v161, v[104:105], off
	v_mov_b32_e32 v105, v65
	v_or_b32_e32 v64, s11, v26
	v_or_b32_e32 v53, s11, v27
	v_lshlrev_b32_e32 v64, 10, v64
	v_lshlrev_b32_e32 v53, 10, v53
	v_or_b32_e32 v64, v52, v64
	v_or_b32_e32 v104, v52, v53
	v_lshl_add_u64 v[106:107], v[64:65], 2, s[12:13]
	v_lshl_add_u64 v[104:105], v[104:105], 2, s[12:13]
	global_load_dword v162, v[106:107], off
	global_load_dword v163, v[104:105], off
	v_mov_b32_e32 v105, v65
	v_or_b32_e32 v64, s11, v28
	v_or_b32_e32 v53, s11, v29
	v_lshlrev_b32_e32 v64, 10, v64
	v_lshlrev_b32_e32 v53, 10, v53
	v_or_b32_e32 v64, v52, v64
	v_or_b32_e32 v104, v52, v53
	v_lshl_add_u64 v[106:107], v[64:65], 2, s[12:13]
	v_lshl_add_u64 v[104:105], v[104:105], 2, s[12:13]
	global_load_dword v164, v[106:107], off
	global_load_dword v165, v[104:105], off
	v_mov_b32_e32 v105, v65
	v_or_b32_e32 v64, s11, v30
	v_or_b32_e32 v53, s11, v31
	v_lshlrev_b32_e32 v64, 10, v64
	v_lshlrev_b32_e32 v53, 10, v53
	v_or_b32_e32 v64, v52, v64
	v_or_b32_e32 v104, v52, v53
	v_lshl_add_u64 v[106:107], v[64:65], 2, s[12:13]
	v_lshl_add_u64 v[104:105], v[104:105], 2, s[12:13]
	global_load_dword v166, v[106:107], off
	global_load_dword v167, v[104:105], off
	v_mov_b32_e32 v105, v65
	v_or_b32_e32 v64, s11, v32
	v_or_b32_e32 v53, s11, v33
	v_lshlrev_b32_e32 v64, 10, v64
	v_lshlrev_b32_e32 v53, 10, v53
	v_or_b32_e32 v64, v52, v64
	v_or_b32_e32 v104, v52, v53
	v_lshl_add_u64 v[106:107], v[64:65], 2, s[12:13]
	v_lshl_add_u64 v[104:105], v[104:105], 2, s[12:13]
	global_load_dword v168, v[106:107], off
	global_load_dword v169, v[104:105], off
	v_mov_b32_e32 v105, v65
	v_or_b32_e32 v64, s11, v34
	v_or_b32_e32 v53, s11, v35
	v_lshlrev_b32_e32 v64, 10, v64
	v_lshlrev_b32_e32 v53, 10, v53
	v_or_b32_e32 v64, v52, v64
	v_or_b32_e32 v104, v52, v53
	v_lshl_add_u64 v[106:107], v[64:65], 2, s[12:13]
	v_lshl_add_u64 v[104:105], v[104:105], 2, s[12:13]
	global_load_dword v170, v[106:107], off
	global_load_dword v171, v[104:105], off
	v_mov_b32_e32 v105, v65
	v_or_b32_e32 v64, s11, v36
	v_or_b32_e32 v53, s11, v37
	v_lshlrev_b32_e32 v64, 10, v64
	v_lshlrev_b32_e32 v53, 10, v53
	v_or_b32_e32 v64, v52, v64
	v_or_b32_e32 v104, v52, v53
	v_lshl_add_u64 v[106:107], v[64:65], 2, s[12:13]
	v_lshl_add_u64 v[104:105], v[104:105], 2, s[12:13]
	global_load_dword v172, v[106:107], off
	global_load_dword v173, v[104:105], off
	v_mov_b32_e32 v105, v65
	v_or_b32_e32 v64, s11, v38
	v_or_b32_e32 v53, s11, v39
	v_lshlrev_b32_e32 v64, 10, v64
	v_lshlrev_b32_e32 v53, 10, v53
	v_or_b32_e32 v64, v52, v64
	v_or_b32_e32 v104, v52, v53
	v_lshl_add_u64 v[106:107], v[64:65], 2, s[12:13]
	v_lshl_add_u64 v[104:105], v[104:105], 2, s[12:13]
	global_load_dword v174, v[106:107], off
	global_load_dword v175, v[104:105], off
	v_mov_b32_e32 v105, v65
	v_or_b32_e32 v64, s11, v40
	v_or_b32_e32 v53, s11, v41
	v_lshlrev_b32_e32 v64, 10, v64
	v_lshlrev_b32_e32 v53, 10, v53
	v_or_b32_e32 v64, v52, v64
	v_or_b32_e32 v104, v52, v53
	v_lshl_add_u64 v[106:107], v[64:65], 2, s[12:13]
	v_lshl_add_u64 v[104:105], v[104:105], 2, s[12:13]
	global_load_dword v176, v[106:107], off
	global_load_dword v177, v[104:105], off
	v_mov_b32_e32 v105, v65
	v_or_b32_e32 v64, s11, v42
	v_or_b32_e32 v53, s11, v43
	v_lshlrev_b32_e32 v64, 10, v64
	v_lshlrev_b32_e32 v53, 10, v53
	v_or_b32_e32 v64, v52, v64
	v_or_b32_e32 v104, v52, v53
	v_lshl_add_u64 v[106:107], v[64:65], 2, s[12:13]
	v_lshl_add_u64 v[104:105], v[104:105], 2, s[12:13]
	global_load_dword v178, v[106:107], off
	global_load_dword v179, v[104:105], off
	v_mov_b32_e32 v105, v65
	v_or_b32_e32 v64, s11, v44
	v_or_b32_e32 v53, s11, v45
	v_lshlrev_b32_e32 v64, 10, v64
	v_lshlrev_b32_e32 v53, 10, v53
	v_or_b32_e32 v64, v52, v64
	v_or_b32_e32 v104, v52, v53
	v_lshl_add_u64 v[106:107], v[64:65], 2, s[12:13]
	v_lshl_add_u64 v[104:105], v[104:105], 2, s[12:13]
	global_load_dword v180, v[106:107], off
	global_load_dword v181, v[104:105], off
	v_mov_b32_e32 v105, v65
	v_or_b32_e32 v64, s11, v46
	v_or_b32_e32 v53, s11, v47
	v_lshlrev_b32_e32 v64, 10, v64
	v_lshlrev_b32_e32 v53, 10, v53
	v_or_b32_e32 v64, v52, v64
	v_or_b32_e32 v104, v52, v53
	v_lshl_add_u64 v[106:107], v[64:65], 2, s[12:13]
	v_lshl_add_u64 v[104:105], v[104:105], 2, s[12:13]
	global_load_dword v182, v[106:107], off
	global_load_dword v183, v[104:105], off
	v_mov_b32_e32 v105, v65
	v_or_b32_e32 v64, s11, v48
	v_or_b32_e32 v53, s11, v49
	v_lshlrev_b32_e32 v64, 10, v64
	v_lshlrev_b32_e32 v53, 10, v53
	v_or_b32_e32 v64, v52, v64
	v_or_b32_e32 v104, v52, v53
	v_lshl_add_u64 v[106:107], v[64:65], 2, s[12:13]
	v_lshl_add_u64 v[104:105], v[104:105], 2, s[12:13]
	global_load_dword v184, v[106:107], off
	global_load_dword v185, v[104:105], off
	v_mov_b32_e32 v105, v65
	v_or_b32_e32 v64, s11, v50
	v_or_b32_e32 v53, s11, v51
	v_lshlrev_b32_e32 v64, 10, v64
	v_lshlrev_b32_e32 v53, 10, v53
	v_or_b32_e32 v64, v52, v64
	v_or_b32_e32 v104, v52, v53
	v_lshl_add_u64 v[52:53], v[64:65], 2, s[12:13]
	v_lshl_add_u64 v[104:105], v[104:105], 2, s[12:13]
	global_load_dword v186, v[52:53], off
	s_nop 0
	global_load_dword v187, v[104:105], off
	s_mov_b32 s11, s19
	v_writelane_b32 v254, s10, 58
	s_waitcnt vmcnt(0)
; __device__ __forceinline__ unsigned cvt_pk_f16(float lo, float hi) { f32x2_t v = {lo, hi}; f16x2_t h = __builtin_convertvector(v, f16x2_t); return __builtin_bit_cast(unsigned, h); }
; #define LAS __attribute__((address_space(3)))
; __device__ __forceinline__ unsigned pk2(float lo, float hi) { return pg8::cvt_pk_bf16(lo, hi); }
; template <bool F16 = false> __device__ __forceinline__ void tr_item(const float* W, int N, bf16* WT, int ldk, int koff, int k0, int n0, int drow0, LAS float* scr, int lane) {
;     ...
;     for (int i = 0; i < 32; ++i) { const int kk = 2 * i + (lane >> 5); scr[kk * 33 + (lane & 31)] = W[(size_t)(k0 + kk) * N + n0 + (lane & 31)]; }
;     asm volatile("s_waitcnt lgkmcnt(0)" ::: "memory");
;     const int c = lane & 7;
; #pragma unroll
;     for (int j = 0; j < 4; ++j) { const int n = (lane >> 3) + 8 * j; const LAS float* s = scr + (8 * c) * 33 + n;
;         u32x4 o;
;         if constexpr (F16) { o.x = pg8::cvt_pk_f16(s[0 * 33], s[1 * 33]); o.y = pg8::cvt_pk_f16(s[2 * 33], s[3 * 33]); o.z = pg8::cvt_pk_f16(s[4 * 33], s[5 * 33]); o.w = pg8::cvt_pk_f16(s[6 * 33], s[7 * 33]); }
;         else { o.x = pk2(s[0 * 33], s[1 * 33]); o.y = pk2(s[2 * 33], s[3 * 33]); o.z = pk2(s[4 * 33], s[5 * 33]); o.w = pk2(s[6 * 33], s[7 * 33]); }
;         *(u32x4*)(WT + (size_t)(drow0 + n) * ldk + koff + k0 + 8 * c) = o; }
;     asm volatile("s_waitcnt lgkmcnt(0)" ::: "memory");
; __device__ __forceinline__ void convert_layer(const Args& a, int l, LAS unsigned char* lds, int gw, int NGW, int lane, int wave, bool gates = true) {
;     ...
;         if (r < I_SQ) { tr_item<true>(w_pg, DM, (bf16*)(ws + WS_WG), 1024, 0, 64 * (r >> 5), 32 * (r & 31), 32 * (r & 31), scr, lane); continue; } r -= I_SQ;
	v_add_u32_e32 v103, v56, v67
	ds_write_b32 v103, v156
	v_add_u32_e32 v53, v56, v68
	ds_write_b32 v53, v157
	v_add_u32_e32 v103, v56, v69
	ds_write_b32 v103, v158
	v_add_u32_e32 v53, v56, v70
	ds_write_b32 v53, v159
	v_add_u32_e32 v103, v56, v71
	ds_write_b32 v103, v160
	v_add_u32_e32 v53, v56, v72
	ds_write_b32 v53, v161
	v_add_u32_e32 v103, v56, v73
	ds_write_b32 v103, v162
	v_add_u32_e32 v53, v56, v74
	ds_write_b32 v53, v163
	v_add_u32_e32 v103, v56, v75
	ds_write_b32 v103, v164
	v_add_u32_e32 v53, v56, v76
	ds_write_b32 v53, v165
	v_add_u32_e32 v103, v56, v77
	ds_write_b32 v103, v166
	v_add_u32_e32 v53, v56, v78
	ds_write_b32 v53, v167
	v_add_u32_e32 v103, v56, v79
	ds_write_b32 v103, v168
	v_add_u32_e32 v53, v56, v80
	ds_write_b32 v53, v169
	v_add_u32_e32 v103, v56, v81
	ds_write_b32 v103, v170
	v_add_u32_e32 v53, v56, v82
	ds_write_b32 v53, v171
	v_add_u32_e32 v103, v56, v83
	ds_write_b32 v103, v172
	v_add_u32_e32 v53, v56, v84
	ds_write_b32 v53, v173
	v_add_u32_e32 v103, v56, v85
	ds_write_b32 v103, v174
	v_add_u32_e32 v53, v56, v86
	ds_write_b32 v53, v175
	v_add_u32_e32 v103, v56, v87
	ds_write_b32 v103, v176
	v_add_u32_e32 v53, v56, v88
	ds_write_b32 v53, v177
	v_add_u32_e32 v103, v56, v89
	ds_write_b32 v103, v178
	v_add_u32_e32 v53, v56, v90
	ds_write_b32 v53, v179
	v_add_u32_e32 v103, v56, v91
	ds_write_b32 v103, v180
	v_add_u32_e32 v53, v56, v92
	ds_write_b32 v53, v181
	v_add_u32_e32 v103, v56, v93
	ds_write_b32 v103, v182
	v_add_u32_e32 v53, v56, v94
	ds_write_b32 v53, v183
	v_add_u32_e32 v103, v56, v95
	ds_write_b32 v103, v184
	v_add_u32_e32 v53, v56, v96
	ds_write_b32 v53, v185
	v_add_u32_e32 v64, v56, v97
	ds_write_b32 v64, v186
	v_add_u32_e32 v52, v56, v98
	ds_write_b32 v52, v187
	s_waitcnt lgkmcnt(0)
	ds_read2_b32 v[108:109], v58 offset0:33 offset1:41
	ds_read2_b32 v[110:111], v58 offset1:8
	ds_read2_b32 v[112:113], v58 offset0:66 offset1:74
	ds_read2_b32 v[114:115], v58 offset0:99 offset1:107
	ds_read2_b32 v[116:117], v58 offset0:132 offset1:140
	ds_read2_b32 v[118:119], v58 offset0:165 offset1:173
	ds_read2_b32 v[120:121], v58 offset0:198 offset1:206
	ds_read2_b32 v[122:123], v58 offset0:231 offset1:239
	v_lshl_add_u64 v[52:53], v[4:5], 0, s[18:19]
	v_lshlrev_b32_e32 v64, 9, v102
	s_waitcnt lgkmcnt(6)
	v_cvt_pk_bf16_f32 v104, v110, v108
	s_waitcnt lgkmcnt(4)
	v_cvt_pk_bf16_f32 v105, v112, v114
	s_waitcnt lgkmcnt(2)
	v_cvt_pk_bf16_f32 v106, v116, v118
	s_waitcnt lgkmcnt(0)
	v_cvt_pk_bf16_f32 v107, v120, v122
	v_lshl_add_u64 v[124:125], v[52:53], 0, v[64:65]
	v_lshlrev_b32_e32 v64, 9, v101
	global_store_dwordx4 v[124:125], v[104:107], off
	v_writelane_b32 v254, s11, 59
	s_mov_b64 s[18:19], 0
	v_cvt_pk_bf16_f32 v104, v111, v109
	v_cvt_pk_bf16_f32 v105, v113, v115
	v_cvt_pk_bf16_f32 v106, v117, v119
	v_cvt_pk_bf16_f32 v107, v121, v123
	v_lshl_add_u64 v[108:109], v[52:53], 0, v[64:65]
	global_store_dwordx4 v[108:109], v[104:107], off
	ds_read2_b32 v[108:109], v58 offset0:49 offset1:57
	ds_read2_b32 v[110:111], v58 offset0:16 offset1:24
	ds_read2_b32 v[112:113], v58 offset0:82 offset1:90
	ds_read2_b32 v[114:115], v58 offset0:115 offset1:123
	ds_read2_b32 v[116:117], v58 offset0:148 offset1:156
	ds_read2_b32 v[118:119], v58 offset0:181 offset1:189
	ds_read2_b32 v[120:121], v58 offset0:214 offset1:222
	ds_read2_b32 v[122:123], v58 offset0:247 offset1:255
	v_lshlrev_b32_e32 v64, 9, v100
	s_waitcnt lgkmcnt(6)
	v_cvt_pk_bf16_f32 v104, v110, v108
	s_waitcnt lgkmcnt(4)
	v_cvt_pk_bf16_f32 v105, v112, v114
	s_waitcnt lgkmcnt(2)
	v_cvt_pk_bf16_f32 v106, v116, v118
	s_waitcnt lgkmcnt(0)
	v_cvt_pk_bf16_f32 v107, v120, v122
	v_lshl_add_u64 v[124:125], v[52:53], 0, v[64:65]
	v_lshlrev_b32_e32 v64, 9, v99
	global_store_dwordx4 v[124:125], v[104:107], off
	v_lshl_add_u64 v[52:53], v[52:53], 0, v[64:65]
	s_nop 0
	v_cvt_pk_bf16_f32 v104, v111, v109
	v_cvt_pk_bf16_f32 v105, v113, v115
	v_cvt_pk_bf16_f32 v106, v117, v119
	v_cvt_pk_bf16_f32 v107, v121, v123
	global_store_dwordx4 v[52:53], v[104:107], off
	s_waitcnt lgkmcnt(0)
.LBB0_616:
	s_andn2_b64 vcc, exec, s[18:19]
	s_cbranch_vccnz .LBB0_618
	s_add_i32 s11, s37, 0x400
	s_and_b32 s11, s11, 0x7fffffc0
	v_readlane_b32 s18, v254, 58
	v_readlane_b32 s19, v254, 59
	s_lshl_b32 s18, s10, 2
	v_or_b32_e32 v64, s11, v0
	v_lshl_add_u64 v[52:53], v[6:7], 0, s[18:19]
	v_or_b32_e32 v104, s11, v1
	v_mov_b32_e32 v105, v65
	v_lshlrev_b64 v[106:107], 12, v[64:65]
	v_lshlrev_b64 v[104:105], 12, v[104:105]
	v_lshl_add_u64 v[106:107], v[52:53], 0, v[106:107]
	v_lshl_add_u64 v[104:105], v[52:53], 0, v[104:105]
	global_load_dword v156, v[106:107], off
	global_load_dword v157, v[104:105], off
	v_mov_b32_e32 v105, v65
	s_lshl_b32 s18, s11, 1
	v_or_b32_e32 v64, s11, v22
	v_or_b32_e32 v104, s11, v23
	v_lshlrev_b64 v[106:107], 12, v[64:65]
	v_lshlrev_b64 v[104:105], 12, v[104:105]
	v_lshl_add_u64 v[106:107], v[52:53], 0, v[106:107]
	v_lshl_add_u64 v[104:105], v[52:53], 0, v[104:105]
	global_load_dword v158, v[106:107], off
	global_load_dword v159, v[104:105], off
	v_mov_b32_e32 v105, v65
	v_or_b32_e32 v64, s11, v24
	v_or_b32_e32 v104, s11, v25
	v_lshlrev_b64 v[106:107], 12, v[64:65]
	v_lshlrev_b64 v[104:105], 12, v[104:105]
	v_lshl_add_u64 v[106:107], v[52:53], 0, v[106:107]
	v_lshl_add_u64 v[104:105], v[52:53], 0, v[104:105]
	global_load_dword v160, v[106:107], off
	global_load_dword v161, v[104:105], off
	v_mov_b32_e32 v105, v65
	v_or_b32_e32 v64, s11, v26
	v_or_b32_e32 v104, s11, v27
	v_lshlrev_b64 v[106:107], 12, v[64:65]
	v_lshlrev_b64 v[104:105], 12, v[104:105]
	v_lshl_add_u64 v[106:107], v[52:53], 0, v[106:107]
	v_lshl_add_u64 v[104:105], v[52:53], 0, v[104:105]
	global_load_dword v162, v[106:107], off
; #define LAS __attribute__((address_space(3)))
; template <bool F16 = false> __device__ __forceinline__ void tr_item(const float* W, int N, bf16* WT, int ldk, int koff, int k0, int n0, int drow0, LAS float* scr, int lane) {
; #pragma unroll 16
;     for (int i = 0; i < 32; ++i) { const int kk = 2 * i + (lane >> 5); scr[kk * 33 + (lane & 31)] = W[(size_t)(k0 + kk) * N + n0 + (lane & 31)]; }
; __device__ __forceinline__ void convert_layer(const Args& a, int l, LAS unsigned char* lds, int gw, int NGW, int lane, int wave, bool gates = true) {
;     ...
;         if (r < I_SQ) { tr_item<true>(w_pg, DM, (bf16*)(ws + WS_WG), 1024, 0, 64 * (r >> 5), 32 * (r & 31), 32 * (r & 31), scr, lane); continue; } r -= I_SQ;
	global_load_dword v163, v[104:105], off
	v_mov_b32_e32 v105, v65
	v_or_b32_e32 v64, s11, v28
	v_or_b32_e32 v104, s11, v29
	v_lshlrev_b64 v[106:107], 12, v[64:65]
	v_lshlrev_b64 v[104:105], 12, v[104:105]
	v_lshl_add_u64 v[106:107], v[52:53], 0, v[106:107]
	v_lshl_add_u64 v[104:105], v[52:53], 0, v[104:105]
	global_load_dword v164, v[106:107], off
	global_load_dword v165, v[104:105], off
	v_mov_b32_e32 v105, v65
	v_or_b32_e32 v64, s11, v30
	v_or_b32_e32 v104, s11, v31
	v_lshlrev_b64 v[106:107], 12, v[64:65]
	v_lshlrev_b64 v[104:105], 12, v[104:105]
	v_lshl_add_u64 v[106:107], v[52:53], 0, v[106:107]
	v_lshl_add_u64 v[104:105], v[52:53], 0, v[104:105]
	global_load_dword v166, v[106:107], off
	global_load_dword v167, v[104:105], off
	v_mov_b32_e32 v105, v65
	v_or_b32_e32 v64, s11, v32
	v_or_b32_e32 v104, s11, v33
	v_lshlrev_b64 v[106:107], 12, v[64:65]
	v_lshlrev_b64 v[104:105], 12, v[104:105]
	v_lshl_add_u64 v[106:107], v[52:53], 0, v[106:107]
	v_lshl_add_u64 v[104:105], v[52:53], 0, v[104:105]
	global_load_dword v168, v[106:107], off
	global_load_dword v169, v[104:105], off
	v_mov_b32_e32 v105, v65
	v_or_b32_e32 v64, s11, v34
	v_or_b32_e32 v104, s11, v35
	v_lshlrev_b64 v[106:107], 12, v[64:65]
	v_lshlrev_b64 v[104:105], 12, v[104:105]
	v_lshl_add_u64 v[106:107], v[52:53], 0, v[106:107]
	v_lshl_add_u64 v[104:105], v[52:53], 0, v[104:105]
	global_load_dword v170, v[106:107], off
	global_load_dword v171, v[104:105], off
	v_mov_b32_e32 v105, v65
	v_or_b32_e32 v64, s11, v36
	v_or_b32_e32 v104, s11, v37
	v_lshlrev_b64 v[106:107], 12, v[64:65]
	v_lshlrev_b64 v[104:105], 12, v[104:105]
	v_lshl_add_u64 v[106:107], v[52:53], 0, v[106:107]
	v_lshl_add_u64 v[104:105], v[52:53], 0, v[104:105]
	global_load_dword v172, v[106:107], off
	global_load_dword v173, v[104:105], off
	v_mov_b32_e32 v105, v65
	v_or_b32_e32 v64, s11, v38
	v_or_b32_e32 v104, s11, v39
	v_lshlrev_b64 v[106:107], 12, v[64:65]
	v_lshlrev_b64 v[104:105], 12, v[104:105]
	v_lshl_add_u64 v[106:107], v[52:53], 0, v[106:107]
	v_lshl_add_u64 v[104:105], v[52:53], 0, v[104:105]
	global_load_dword v174, v[106:107], off
	global_load_dword v175, v[104:105], off
	v_mov_b32_e32 v105, v65
	v_or_b32_e32 v64, s11, v40
	v_or_b32_e32 v104, s11, v41
	v_lshlrev_b64 v[106:107], 12, v[64:65]
	v_lshlrev_b64 v[104:105], 12, v[104:105]
	v_lshl_add_u64 v[106:107], v[52:53], 0, v[106:107]
	v_lshl_add_u64 v[104:105], v[52:53], 0, v[104:105]
	global_load_dword v176, v[106:107], off
	global_load_dword v177, v[104:105], off
	v_mov_b32_e32 v105, v65
	v_or_b32_e32 v64, s11, v42
	v_or_b32_e32 v104, s11, v43
	v_lshlrev_b64 v[106:107], 12, v[64:65]
	v_lshlrev_b64 v[104:105], 12, v[104:105]
	v_lshl_add_u64 v[106:107], v[52:53], 0, v[106:107]
	v_lshl_add_u64 v[104:105], v[52:53], 0, v[104:105]
	global_load_dword v178, v[106:107], off
	global_load_dword v179, v[104:105], off
	v_mov_b32_e32 v105, v65
	v_or_b32_e32 v64, s11, v44
	v_or_b32_e32 v104, s11, v45
	v_lshlrev_b64 v[106:107], 12, v[64:65]
	v_lshlrev_b64 v[104:105], 12, v[104:105]
	v_lshl_add_u64 v[106:107], v[52:53], 0, v[106:107]
	v_lshl_add_u64 v[104:105], v[52:53], 0, v[104:105]
	global_load_dword v180, v[106:107], off
	global_load_dword v181, v[104:105], off
	v_mov_b32_e32 v105, v65
	v_or_b32_e32 v64, s11, v46
	v_or_b32_e32 v104, s11, v47
	v_lshlrev_b64 v[106:107], 12, v[64:65]
	v_lshlrev_b64 v[104:105], 12, v[104:105]
	v_lshl_add_u64 v[106:107], v[52:53], 0, v[106:107]
	v_lshl_add_u64 v[104:105], v[52:53], 0, v[104:105]
	global_load_dword v182, v[106:107], off
	global_load_dword v183, v[104:105], off
	v_mov_b32_e32 v105, v65
	v_or_b32_e32 v64, s11, v48
	v_or_b32_e32 v104, s11, v49
	v_lshlrev_b64 v[106:107], 12, v[64:65]
	v_lshlrev_b64 v[104:105], 12, v[104:105]
	v_lshl_add_u64 v[106:107], v[52:53], 0, v[106:107]
	v_lshl_add_u64 v[104:105], v[52:53], 0, v[104:105]
	global_load_dword v184, v[106:107], off
	global_load_dword v185, v[104:105], off
	v_mov_b32_e32 v105, v65
	v_or_b32_e32 v104, s11, v51
	v_or_b32_e32 v64, s11, v50
	v_lshlrev_b64 v[104:105], 12, v[104:105]
	v_lshlrev_b64 v[106:107], 12, v[64:65]
	v_lshl_add_u64 v[106:107], v[52:53], 0, v[106:107]
	v_lshl_add_u64 v[52:53], v[52:53], 0, v[104:105]
	global_load_dword v186, v[106:107], off
	s_nop 0
	global_load_dword v187, v[52:53], off
	s_mov_b32 s11, s19
	v_writelane_b32 v254, s10, 58
	s_waitcnt vmcnt(0)
; __device__ __forceinline__ unsigned cvt_pk_f16(float lo, float hi) { f32x2_t v = {lo, hi}; f16x2_t h = __builtin_convertvector(v, f16x2_t); return __builtin_bit_cast(unsigned, h); }
; #define LAS __attribute__((address_space(3)))
; __device__ __forceinline__ unsigned pk2(float lo, float hi) { return pg8::cvt_pk_bf16(lo, hi); }
; template <bool F16 = false> __device__ __forceinline__ void tr_item(const float* W, int N, bf16* WT, int ldk, int koff, int k0, int n0, int drow0, LAS float* scr, int lane) {
;     ...
;     for (int i = 0; i < 32; ++i) { const int kk = 2 * i + (lane >> 5); scr[kk * 33 + (lane & 31)] = W[(size_t)(k0 + kk) * N + n0 + (lane & 31)]; }
;     asm volatile("s_waitcnt lgkmcnt(0)" ::: "memory");
;     const int c = lane & 7;
; #pragma unroll
;     for (int j = 0; j < 4; ++j) { const int n = (lane >> 3) + 8 * j; const LAS float* s = scr + (8 * c) * 33 + n;
;         u32x4 o;
;         if constexpr (F16) { o.x = pg8::cvt_pk_f16(s[0 * 33], s[1 * 33]); o.y = pg8::cvt_pk_f16(s[2 * 33], s[3 * 33]); o.z = pg8::cvt_pk_f16(s[4 * 33], s[5 * 33]); o.w = pg8::cvt_pk_f16(s[6 * 33], s[7 * 33]); }
;         else { o.x = pk2(s[0 * 33], s[1 * 33]); o.y = pk2(s[2 * 33], s[3 * 33]); o.z = pk2(s[4 * 33], s[5 * 33]); o.w = pk2(s[6 * 33], s[7 * 33]); }
;         *(u32x4*)(WT + (size_t)(drow0 + n) * ldk + koff + k0 + 8 * c) = o; }
;     asm volatile("s_waitcnt lgkmcnt(0)" ::: "memory");
	v_add_u32_e32 v104, v56, v67
	ds_write_b32 v104, v156
	v_add_u32_e32 v64, v56, v68
	ds_write_b32 v64, v157
	v_add_u32_e32 v104, v56, v69
	ds_write_b32 v104, v158
	v_add_u32_e32 v64, v56, v70
	ds_write_b32 v64, v159
	v_add_u32_e32 v104, v56, v71
	ds_write_b32 v104, v160
	v_add_u32_e32 v64, v56, v72
	ds_write_b32 v64, v161
	v_add_u32_e32 v104, v56, v73
	ds_write_b32 v104, v162
	v_add_u32_e32 v64, v56, v74
	ds_write_b32 v64, v163
	v_add_u32_e32 v104, v56, v75
	ds_write_b32 v104, v164
	v_add_u32_e32 v64, v56, v76
	ds_write_b32 v64, v165
	v_add_u32_e32 v104, v56, v77
	ds_write_b32 v104, v166
	v_add_u32_e32 v64, v56, v78
	ds_write_b32 v64, v167
	v_add_u32_e32 v104, v56, v79
	ds_write_b32 v104, v168
	v_add_u32_e32 v64, v56, v80
	ds_write_b32 v64, v169
	v_add_u32_e32 v104, v56, v81
	ds_write_b32 v104, v170
	v_add_u32_e32 v64, v56, v82
	ds_write_b32 v64, v171
	v_add_u32_e32 v104, v56, v83
	ds_write_b32 v104, v172
	v_add_u32_e32 v64, v56, v84
	ds_write_b32 v64, v173
	v_add_u32_e32 v104, v56, v85
	ds_write_b32 v104, v174
	v_add_u32_e32 v64, v56, v86
	ds_write_b32 v64, v175
	v_add_u32_e32 v104, v56, v87
	ds_write_b32 v104, v176
	v_add_u32_e32 v64, v56, v88
	ds_write_b32 v64, v177
	v_add_u32_e32 v104, v56, v89
	ds_write_b32 v104, v178
	v_add_u32_e32 v64, v56, v90
	ds_write_b32 v64, v179
	v_add_u32_e32 v104, v56, v91
	ds_write_b32 v104, v180
	v_add_u32_e32 v64, v56, v92
	ds_write_b32 v64, v181
	v_add_u32_e32 v104, v56, v93
	ds_write_b32 v104, v182
	v_add_u32_e32 v64, v56, v94
	ds_write_b32 v64, v183
	v_add_u32_e32 v104, v56, v95
	ds_write_b32 v104, v184
	v_add_u32_e32 v64, v56, v96
	ds_write_b32 v64, v185
	v_add_u32_e32 v53, v56, v97
	ds_write_b32 v53, v186
	v_add_u32_e32 v53, v56, v98
	ds_write_b32 v53, v187
	s_waitcnt lgkmcnt(0)
	ds_read2_b32 v[108:109], v58 offset0:33 offset1:41
	ds_read2_b32 v[110:111], v58 offset1:8
	ds_read2_b32 v[112:113], v58 offset0:66 offset1:74
	ds_read2_b32 v[114:115], v58 offset0:99 offset1:107
	ds_read2_b32 v[116:117], v58 offset0:132 offset1:140
	ds_read2_b32 v[118:119], v58 offset0:165 offset1:173
	ds_read2_b32 v[120:121], v58 offset0:198 offset1:206
	ds_read2_b32 v[122:123], v58 offset0:231 offset1:239
	v_lshl_add_u64 v[52:53], v[8:9], 0, s[18:19]
	v_lshlrev_b32_e32 v64, 11, v102
	s_waitcnt lgkmcnt(6)
	v_cvt_pk_f16_f32 v104, v110, v108
	s_waitcnt lgkmcnt(4)
	v_cvt_pk_f16_f32 v105, v112, v114
	s_waitcnt lgkmcnt(2)
	v_cvt_pk_f16_f32 v106, v116, v118
	s_waitcnt lgkmcnt(0)
	v_cvt_pk_f16_f32 v107, v120, v122
	v_lshl_add_u64 v[102:103], v[52:53], 0, v[64:65]
	v_lshlrev_b32_e32 v64, 11, v101
	global_store_dwordx4 v[102:103], v[104:107], off
	v_cvt_pk_f16_f32 v102, v111, v109
	v_cvt_pk_f16_f32 v103, v113, v115
	v_cvt_pk_f16_f32 v104, v117, v119
	v_cvt_pk_f16_f32 v105, v121, v123
	v_lshl_add_u64 v[106:107], v[52:53], 0, v[64:65]
	global_store_dwordx4 v[106:107], v[102:105], off
	ds_read2_b32 v[106:107], v58 offset0:49 offset1:57
	ds_read2_b32 v[108:109], v58 offset0:16 offset1:24
	ds_read2_b32 v[110:111], v58 offset0:82 offset1:90
	ds_read2_b32 v[112:113], v58 offset0:115 offset1:123
	ds_read2_b32 v[114:115], v58 offset0:148 offset1:156
	ds_read2_b32 v[116:117], v58 offset0:181 offset1:189
	ds_read2_b32 v[118:119], v58 offset0:214 offset1:222
	ds_read2_b32 v[120:121], v58 offset0:247 offset1:255
	v_lshlrev_b32_e32 v64, 11, v100
	s_waitcnt lgkmcnt(6)
	v_cvt_pk_f16_f32 v102, v108, v106
	s_waitcnt lgkmcnt(4)
	v_cvt_pk_f16_f32 v103, v110, v112
	s_waitcnt lgkmcnt(2)
	v_cvt_pk_f16_f32 v104, v114, v116
	s_waitcnt lgkmcnt(0)
	v_cvt_pk_f16_f32 v105, v118, v120
	v_lshl_add_u64 v[100:101], v[52:53], 0, v[64:65]
	v_lshlrev_b32_e32 v64, 11, v99
	global_store_dwordx4 v[100:101], v[102:105], off
	v_cvt_pk_f16_f32 v100, v109, v107
	v_cvt_pk_f16_f32 v101, v111, v113
	v_cvt_pk_f16_f32 v102, v115, v117
	v_cvt_pk_f16_f32 v103, v119, v121
	v_lshl_add_u64 v[52:53], v[52:53], 0, v[64:65]
	global_store_dwordx4 v[52:53], v[100:103], off
	s_waitcnt lgkmcnt(0)
	v_writelane_b32 v254, s11, 59

; #define LAS __attribute__((address_space(3)))
; template <bool F16 = false> __device__ __forceinline__ void tr_item(const float* W, int N, bf16* WT, int ldk, int koff, int k0, int n0, int drow0, LAS float* scr, int lane) {
; #pragma unroll 16
;     for (int i = 0; i < 32; ++i) { const int kk = 2 * i + (lane >> 5); scr[kk * 33 + (lane & 31)] = W[(size_t)(k0 + kk) * N + n0 + (lane & 31)]; }
; __device__ __forceinline__ void convert_layer(const Args& a, int l, LAS unsigned char* lds, int gw, int NGW, int lane, int wave, bool gates = true) {
;     ...
;         if (r < I_SQ) { tr_item(w_out, DM, (bf16*)(ws + WS_WO), 1024, 0, 64 * (r >> 5), 32 * (r & 31), 32 * (r & 31), scr, lane); continue; } r -= I_SQ;
.LBB0_619:
	s_andn2_b64 vcc, exec, s[18:19]
	s_cbranch_vccnz .LBB0_621
	s_add_i32 s10, s37, 0x800
	s_and_b32 s11, s10, 0x7fffffc0
	s_and_b32 s10, s31, 0x3e0
	v_or_b32_e32 v52, s11, v1
	v_or_b32_e32 v53, s11, v0
	v_lshlrev_b32_e32 v64, 10, v52
	v_lshlrev_b32_e32 v53, 10, v53
	v_or_b32_e32 v52, s10, v55
	v_or_b32_e32 v100, v52, v64
	v_or_b32_e32 v64, v52, v53
	v_lshl_add_u64 v[102:103], v[64:65], 2, s[8:9]
	v_mov_b32_e32 v101, v65
	v_lshl_add_u64 v[100:101], v[100:101], 2, s[8:9]
	global_load_dword v156, v[102:103], off
	global_load_dword v157, v[100:101], off
	v_mov_b32_e32 v101, v65
	v_readlane_b32 s18, v254, 58
	v_readlane_b32 s19, v254, 59
	s_lshl_b32 s18, s11, 1
	v_or_b32_e32 v64, s11, v22
	v_or_b32_e32 v53, s11, v23
	v_lshlrev_b32_e32 v64, 10, v64
	v_lshlrev_b32_e32 v53, 10, v53
	v_or_b32_e32 v64, v52, v64
	v_or_b32_e32 v100, v52, v53
	v_lshl_add_u64 v[102:103], v[64:65], 2, s[8:9]
	v_lshl_add_u64 v[100:101], v[100:101], 2, s[8:9]
	global_load_dword v158, v[102:103], off
	global_load_dword v159, v[100:101], off
	v_mov_b32_e32 v101, v65
	v_or_b32_e32 v64, s11, v24
	v_or_b32_e32 v53, s11, v25
	v_lshlrev_b32_e32 v64, 10, v64
	v_lshlrev_b32_e32 v53, 10, v53
	v_or_b32_e32 v64, v52, v64
	v_or_b32_e32 v100, v52, v53
	v_lshl_add_u64 v[102:103], v[64:65], 2, s[8:9]
	v_lshl_add_u64 v[100:101], v[100:101], 2, s[8:9]
	global_load_dword v160, v[102:103], off
	global_load_dword v161, v[100:101], off
	v_mov_b32_e32 v101, v65
	v_or_b32_e32 v64, s11, v26
	v_or_b32_e32 v53, s11, v27
	v_lshlrev_b32_e32 v64, 10, v64
	v_lshlrev_b32_e32 v53, 10, v53
	v_or_b32_e32 v64, v52, v64
	v_or_b32_e32 v100, v52, v53
	v_lshl_add_u64 v[102:103], v[64:65], 2, s[8:9]
	v_lshl_add_u64 v[100:101], v[100:101], 2, s[8:9]
	global_load_dword v162, v[102:103], off
	global_load_dword v163, v[100:101], off
	v_mov_b32_e32 v101, v65
	v_or_b32_e32 v64, s11, v28
	v_or_b32_e32 v53, s11, v29
	v_lshlrev_b32_e32 v64, 10, v64
	v_lshlrev_b32_e32 v53, 10, v53
	v_or_b32_e32 v64, v52, v64
	v_or_b32_e32 v100, v52, v53
	v_lshl_add_u64 v[102:103], v[64:65], 2, s[8:9]
	v_lshl_add_u64 v[100:101], v[100:101], 2, s[8:9]
	global_load_dword v164, v[102:103], off
	global_load_dword v165, v[100:101], off
	v_mov_b32_e32 v101, v65
	v_or_b32_e32 v64, s11, v30
	v_or_b32_e32 v53, s11, v31
	v_lshlrev_b32_e32 v64, 10, v64
	v_lshlrev_b32_e32 v53, 10, v53
	v_or_b32_e32 v64, v52, v64
	v_or_b32_e32 v100, v52, v53
	v_lshl_add_u64 v[102:103], v[64:65], 2, s[8:9]
	v_lshl_add_u64 v[100:101], v[100:101], 2, s[8:9]
	global_load_dword v166, v[102:103], off
	global_load_dword v167, v[100:101], off
	v_mov_b32_e32 v101, v65
	v_or_b32_e32 v64, s11, v32
	v_or_b32_e32 v53, s11, v33
	v_lshlrev_b32_e32 v64, 10, v64
	v_lshlrev_b32_e32 v53, 10, v53
	v_or_b32_e32 v64, v52, v64
	v_or_b32_e32 v100, v52, v53
	v_lshl_add_u64 v[102:103], v[64:65], 2, s[8:9]
	v_lshl_add_u64 v[100:101], v[100:101], 2, s[8:9]
	global_load_dword v168, v[102:103], off
	global_load_dword v169, v[100:101], off
	v_mov_b32_e32 v101, v65
	v_or_b32_e32 v64, s11, v34
	v_or_b32_e32 v53, s11, v35
	v_lshlrev_b32_e32 v64, 10, v64
	v_lshlrev_b32_e32 v53, 10, v53
	v_or_b32_e32 v64, v52, v64
	v_or_b32_e32 v100, v52, v53
	v_lshl_add_u64 v[102:103], v[64:65], 2, s[8:9]
	v_lshl_add_u64 v[100:101], v[100:101], 2, s[8:9]
	global_load_dword v170, v[102:103], off
	global_load_dword v171, v[100:101], off
	v_mov_b32_e32 v101, v65
	v_or_b32_e32 v64, s11, v36
	v_or_b32_e32 v53, s11, v37
	v_lshlrev_b32_e32 v64, 10, v64
	v_lshlrev_b32_e32 v53, 10, v53
	v_or_b32_e32 v64, v52, v64
	v_or_b32_e32 v100, v52, v53
	v_lshl_add_u64 v[102:103], v[64:65], 2, s[8:9]
	v_lshl_add_u64 v[100:101], v[100:101], 2, s[8:9]
	global_load_dword v172, v[102:103], off
	global_load_dword v173, v[100:101], off
	v_mov_b32_e32 v101, v65
	v_or_b32_e32 v64, s11, v38
	v_or_b32_e32 v53, s11, v39
	v_lshlrev_b32_e32 v64, 10, v64
	v_lshlrev_b32_e32 v53, 10, v53
	v_or_b32_e32 v64, v52, v64
	v_or_b32_e32 v100, v52, v53
	v_lshl_add_u64 v[102:103], v[64:65], 2, s[8:9]
	v_lshl_add_u64 v[100:101], v[100:101], 2, s[8:9]
	global_load_dword v174, v[102:103], off
	global_load_dword v175, v[100:101], off
	v_mov_b32_e32 v101, v65
	v_or_b32_e32 v64, s11, v40
	v_or_b32_e32 v53, s11, v41
	v_lshlrev_b32_e32 v64, 10, v64
	v_lshlrev_b32_e32 v53, 10, v53
	v_or_b32_e32 v64, v52, v64
	v_or_b32_e32 v100, v52, v53
	v_lshl_add_u64 v[102:103], v[64:65], 2, s[8:9]
	v_lshl_add_u64 v[100:101], v[100:101], 2, s[8:9]
	global_load_dword v176, v[102:103], off
	global_load_dword v177, v[100:101], off
	v_mov_b32_e32 v101, v65
	v_or_b32_e32 v64, s11, v42
	v_or_b32_e32 v53, s11, v43
	v_lshlrev_b32_e32 v64, 10, v64
	v_lshlrev_b32_e32 v53, 10, v53
	v_or_b32_e32 v64, v52, v64
	v_or_b32_e32 v100, v52, v53
	v_lshl_add_u64 v[102:103], v[64:65], 2, s[8:9]
	v_lshl_add_u64 v[100:101], v[100:101], 2, s[8:9]
	global_load_dword v178, v[102:103], off
	global_load_dword v179, v[100:101], off
	v_mov_b32_e32 v101, v65
	v_or_b32_e32 v64, s11, v44
	v_or_b32_e32 v53, s11, v45
	v_lshlrev_b32_e32 v64, 10, v64
	v_lshlrev_b32_e32 v53, 10, v53
	v_or_b32_e32 v64, v52, v64
	v_or_b32_e32 v100, v52, v53
	v_lshl_add_u64 v[102:103], v[64:65], 2, s[8:9]
	v_lshl_add_u64 v[100:101], v[100:101], 2, s[8:9]
	global_load_dword v180, v[102:103], off
	global_load_dword v181, v[100:101], off
	v_mov_b32_e32 v101, v65
	v_or_b32_e32 v64, s11, v46
	v_or_b32_e32 v53, s11, v47
	v_lshlrev_b32_e32 v64, 10, v64
	v_lshlrev_b32_e32 v53, 10, v53
	v_or_b32_e32 v64, v52, v64
	v_or_b32_e32 v100, v52, v53
	v_lshl_add_u64 v[102:103], v[64:65], 2, s[8:9]
	v_lshl_add_u64 v[100:101], v[100:101], 2, s[8:9]
	global_load_dword v182, v[102:103], off
	global_load_dword v183, v[100:101], off
	v_mov_b32_e32 v101, v65
	v_or_b32_e32 v64, s11, v48
	v_or_b32_e32 v53, s11, v49
	v_lshlrev_b32_e32 v64, 10, v64
	v_lshlrev_b32_e32 v53, 10, v53
	v_or_b32_e32 v64, v52, v64
	v_or_b32_e32 v100, v52, v53
	v_lshl_add_u64 v[102:103], v[64:65], 2, s[8:9]
	v_lshl_add_u64 v[100:101], v[100:101], 2, s[8:9]
	global_load_dword v184, v[102:103], off
	global_load_dword v185, v[100:101], off
	v_mov_b32_e32 v101, v65
	v_or_b32_e32 v64, s11, v50
	v_or_b32_e32 v53, s11, v51
	v_lshlrev_b32_e32 v64, 10, v64
	v_lshlrev_b32_e32 v53, 10, v53
	v_or_b32_e32 v64, v52, v64
	v_or_b32_e32 v100, v52, v53
	v_lshl_add_u64 v[52:53], v[64:65], 2, s[8:9]
	v_lshl_add_u64 v[100:101], v[100:101], 2, s[8:9]
	global_load_dword v186, v[52:53], off
	s_nop 0
	global_load_dword v187, v[100:101], off
	s_mov_b32 s11, s19
	v_writelane_b32 v254, s10, 58
	s_waitcnt vmcnt(0)
; __device__ __forceinline__ unsigned cvt_pk_f16(float lo, float hi) { f32x2_t v = {lo, hi}; f16x2_t h = __builtin_convertvector(v, f16x2_t); return __builtin_bit_cast(unsigned, h); }
; #define LAS __attribute__((address_space(3)))
; __device__ __forceinline__ unsigned pk2(float lo, float hi) { return pg8::cvt_pk_bf16(lo, hi); }
; template <bool F16 = false> __device__ __forceinline__ void tr_item(const float* W, int N, bf16* WT, int ldk, int koff, int k0, int n0, int drow0, LAS float* scr, int lane) {
;     ...
;     for (int i = 0; i < 32; ++i) { const int kk = 2 * i + (lane >> 5); scr[kk * 33 + (lane & 31)] = W[(size_t)(k0 + kk) * N + n0 + (lane & 31)]; }
;     asm volatile("s_waitcnt lgkmcnt(0)" ::: "memory");
;     const int c = lane & 7;
; #pragma unroll
;     for (int j = 0; j < 4; ++j) { const int n = (lane >> 3) + 8 * j; const LAS float* s = scr + (8 * c) * 33 + n;
;         u32x4 o;
;         if constexpr (F16) { o.x = pg8::cvt_pk_f16(s[0 * 33], s[1 * 33]); o.y = pg8::cvt_pk_f16(s[2 * 33], s[3 * 33]); o.z = pg8::cvt_pk_f16(s[4 * 33], s[5 * 33]); o.w = pg8::cvt_pk_f16(s[6 * 33], s[7 * 33]); }
;         else { o.x = pk2(s[0 * 33], s[1 * 33]); o.y = pk2(s[2 * 33], s[3 * 33]); o.z = pk2(s[4 * 33], s[5 * 33]); o.w = pk2(s[6 * 33], s[7 * 33]); }
;         *(u32x4*)(WT + (size_t)(drow0 + n) * ldk + koff + k0 + 8 * c) = o; }
;     asm volatile("s_waitcnt lgkmcnt(0)" ::: "memory");
	v_add_u32_e32 v99, v56, v67
	ds_write_b32 v99, v156
	v_add_u32_e32 v53, v56, v68
	ds_write_b32 v53, v157
	v_add_u32_e32 v99, v56, v69
	ds_write_b32 v99, v158
	v_add_u32_e32 v53, v56, v70
	ds_write_b32 v53, v159
	v_add_u32_e32 v99, v56, v71
	ds_write_b32 v99, v160
	v_add_u32_e32 v53, v56, v72
	ds_write_b32 v53, v161
	v_add_u32_e32 v99, v56, v73
	ds_write_b32 v99, v162
	v_add_u32_e32 v53, v56, v74
	ds_write_b32 v53, v163
	v_add_u32_e32 v99, v56, v75
	ds_write_b32 v99, v164
	v_add_u32_e32 v53, v56, v76
	ds_write_b32 v53, v165
	v_add_u32_e32 v99, v56, v77
	ds_write_b32 v99, v166
	v_add_u32_e32 v53, v56, v78
	ds_write_b32 v53, v167
	v_add_u32_e32 v99, v56, v79
	ds_write_b32 v99, v168
	v_add_u32_e32 v53, v56, v80
	ds_write_b32 v53, v169
	v_add_u32_e32 v99, v56, v81
	ds_write_b32 v99, v170
	v_add_u32_e32 v53, v56, v82
	ds_write_b32 v53, v171
	v_add_u32_e32 v99, v56, v83
	ds_write_b32 v99, v172
	v_add_u32_e32 v53, v56, v84
	ds_write_b32 v53, v173
	v_add_u32_e32 v99, v56, v85
	ds_write_b32 v99, v174
	v_add_u32_e32 v53, v56, v86
	ds_write_b32 v53, v175
	v_add_u32_e32 v99, v56, v87
	ds_write_b32 v99, v176
	v_add_u32_e32 v53, v56, v88
	ds_write_b32 v53, v177
	v_add_u32_e32 v99, v56, v89
	ds_write_b32 v99, v178
	v_add_u32_e32 v53, v56, v90
	ds_write_b32 v53, v179
	v_add_u32_e32 v99, v56, v91
	ds_write_b32 v99, v180
	v_add_u32_e32 v53, v56, v92
	ds_write_b32 v53, v181
	v_add_u32_e32 v99, v56, v93
	ds_write_b32 v99, v182
	v_add_u32_e32 v53, v56, v94
	ds_write_b32 v53, v183
	v_add_u32_e32 v99, v56, v95
	ds_write_b32 v99, v184
	v_add_u32_e32 v53, v56, v96
	ds_write_b32 v53, v185
	v_add_u32_e32 v64, v56, v97
	ds_write_b32 v64, v186
	v_add_u32_e32 v52, v56, v98
	ds_write_b32 v52, v187
	s_waitcnt lgkmcnt(0)
	ds_read2_b32 v[104:105], v58 offset0:33 offset1:41
	ds_read2_b32 v[106:107], v58 offset1:8
	ds_read2_b32 v[108:109], v58 offset0:66 offset1:74
	ds_read2_b32 v[110:111], v58 offset0:99 offset1:107
	ds_read2_b32 v[112:113], v58 offset0:132 offset1:140
	ds_read2_b32 v[114:115], v58 offset0:165 offset1:173
	ds_read2_b32 v[116:117], v58 offset0:198 offset1:206
	ds_read2_b32 v[118:119], v58 offset0:231 offset1:239
	v_or_b32_e32 v64, s10, v57
	v_lshl_add_u64 v[52:53], v[10:11], 0, s[18:19]
	v_lshlrev_b32_e32 v64, 11, v64
	v_lshl_add_u64 v[120:121], v[52:53], 0, v[64:65]
	v_or_b32_e32 v64, s10, v59
	s_waitcnt lgkmcnt(6)
	v_cvt_pk_bf16_f32 v100, v106, v104
	s_waitcnt lgkmcnt(4)
	v_cvt_pk_bf16_f32 v101, v108, v110
	s_waitcnt lgkmcnt(2)
	v_cvt_pk_bf16_f32 v102, v112, v114
	s_waitcnt lgkmcnt(0)
	v_cvt_pk_bf16_f32 v103, v116, v118
	v_lshlrev_b32_e32 v64, 11, v64
	global_store_dwordx4 v[120:121], v[100:103], off
	v_writelane_b32 v254, s11, 59
	s_nop 0
	v_cvt_pk_bf16_f32 v100, v107, v105
	v_cvt_pk_bf16_f32 v101, v109, v111
	v_cvt_pk_bf16_f32 v102, v113, v115
	v_cvt_pk_bf16_f32 v103, v117, v119
	v_lshl_add_u64 v[104:105], v[52:53], 0, v[64:65]
	global_store_dwordx4 v[104:105], v[100:103], off
	ds_read2_b32 v[104:105], v58 offset0:49 offset1:57
	ds_read2_b32 v[106:107], v58 offset0:16 offset1:24
	ds_read2_b32 v[108:109], v58 offset0:82 offset1:90
	ds_read2_b32 v[110:111], v58 offset0:115 offset1:123
	ds_read2_b32 v[112:113], v58 offset0:148 offset1:156
	ds_read2_b32 v[114:115], v58 offset0:181 offset1:189
	ds_read2_b32 v[116:117], v58 offset0:214 offset1:222
	ds_read2_b32 v[118:119], v58 offset0:247 offset1:255
	v_or_b32_e32 v64, s10, v60
	v_lshlrev_b32_e32 v64, 11, v64
	v_lshl_add_u64 v[120:121], v[52:53], 0, v[64:65]
	v_or_b32_e32 v64, s10, v61
	s_waitcnt lgkmcnt(6)
	v_cvt_pk_bf16_f32 v100, v106, v104
	s_waitcnt lgkmcnt(4)
	v_cvt_pk_bf16_f32 v101, v108, v110
	s_waitcnt lgkmcnt(2)
	v_cvt_pk_bf16_f32 v102, v112, v114
	s_waitcnt lgkmcnt(0)
	v_cvt_pk_bf16_f32 v103, v116, v118
	v_lshlrev_b32_e32 v64, 11, v64
	global_store_dwordx4 v[120:121], v[100:103], off
	v_lshl_add_u64 v[52:53], v[52:53], 0, v[64:65]
	s_nop 0
	v_cvt_pk_bf16_f32 v100, v107, v105
	v_cvt_pk_bf16_f32 v101, v109, v111
	v_cvt_pk_bf16_f32 v102, v113, v115
	v_cvt_pk_bf16_f32 v103, v117, v119
	global_store_dwordx4 v[52:53], v[100:103], off
	s_waitcnt lgkmcnt(0)

; #define LAS __attribute__((address_space(3)))
; template <bool F16 = false> __device__ __forceinline__ void tr_item(const float* W, int N, bf16* WT, int ldk, int koff, int k0, int n0, int drow0, LAS float* scr, int lane) {
; #pragma unroll 16
;     for (int i = 0; i < 32; ++i) { const int kk = 2 * i + (lane >> 5); scr[kk * 33 + (lane & 31)] = W[(size_t)(k0 + kk) * N + n0 + (lane & 31)]; }
; __device__ __forceinline__ void convert_layer(const Args& a, int l, LAS unsigned char* lds, int gw, int NGW, int lane, int wave, bool gates = true) {
;     ...
;         if (r < I_SQ) { tr_item(w_pb, DM, (bf16*)(ws + WS_W2), 2048, 1024, 64 * (r >> 5), 32 * (r & 31), 32 * (r & 31), scr, lane); continue; } r -= I_SQ;
.LBB0_622:
	s_andn2_b64 vcc, exec, s[18:19]
	s_cbranch_vccnz .LBB0_624
	s_add_i32 s10, s37, 0xc00
	s_and_b32 s11, s10, 0x7fffffc0
	s_and_b32 s10, s31, 0x3e0
	v_or_b32_e32 v52, s11, v1
	v_or_b32_e32 v53, s11, v0
	v_lshlrev_b32_e32 v64, 10, v52
	v_lshlrev_b32_e32 v53, 10, v53
	v_or_b32_e32 v52, s10, v55
	v_or_b32_e32 v100, v52, v64
	v_or_b32_e32 v64, v52, v53
	v_lshl_add_u64 v[102:103], v[64:65], 2, s[4:5]
	v_mov_b32_e32 v101, v65
	v_lshl_add_u64 v[100:101], v[100:101], 2, s[4:5]
	global_load_dword v156, v[102:103], off
	global_load_dword v157, v[100:101], off
	v_mov_b32_e32 v101, v65
	v_readlane_b32 s18, v254, 58
	v_readlane_b32 s19, v254, 59
	s_lshl_b32 s18, s11, 1
	v_or_b32_e32 v64, s11, v22
	v_or_b32_e32 v53, s11, v23
	v_lshlrev_b32_e32 v64, 10, v64
	v_lshlrev_b32_e32 v53, 10, v53
	v_or_b32_e32 v64, v52, v64
	v_or_b32_e32 v100, v52, v53
	v_lshl_add_u64 v[102:103], v[64:65], 2, s[4:5]
	v_lshl_add_u64 v[100:101], v[100:101], 2, s[4:5]
	global_load_dword v158, v[102:103], off
	global_load_dword v159, v[100:101], off
	v_mov_b32_e32 v101, v65
	v_or_b32_e32 v64, s11, v24
	v_or_b32_e32 v53, s11, v25
	v_lshlrev_b32_e32 v64, 10, v64
	v_lshlrev_b32_e32 v53, 10, v53
	v_or_b32_e32 v64, v52, v64
	v_or_b32_e32 v100, v52, v53
	v_lshl_add_u64 v[102:103], v[64:65], 2, s[4:5]
	v_lshl_add_u64 v[100:101], v[100:101], 2, s[4:5]
	global_load_dword v160, v[102:103], off
	global_load_dword v161, v[100:101], off
	v_mov_b32_e32 v101, v65
	v_or_b32_e32 v64, s11, v26
	v_or_b32_e32 v53, s11, v27
	v_lshlrev_b32_e32 v64, 10, v64
	v_lshlrev_b32_e32 v53, 10, v53
	v_or_b32_e32 v64, v52, v64
	v_or_b32_e32 v100, v52, v53
	v_lshl_add_u64 v[102:103], v[64:65], 2, s[4:5]
	v_lshl_add_u64 v[100:101], v[100:101], 2, s[4:5]
	global_load_dword v162, v[102:103], off
	global_load_dword v163, v[100:101], off
	v_mov_b32_e32 v101, v65
	v_or_b32_e32 v64, s11, v28
	v_or_b32_e32 v53, s11, v29
	v_lshlrev_b32_e32 v64, 10, v64
	v_lshlrev_b32_e32 v53, 10, v53
	v_or_b32_e32 v64, v52, v64
	v_or_b32_e32 v100, v52, v53
	v_lshl_add_u64 v[102:103], v[64:65], 2, s[4:5]
	v_lshl_add_u64 v[100:101], v[100:101], 2, s[4:5]
	global_load_dword v164, v[102:103], off
	global_load_dword v165, v[100:101], off
	v_mov_b32_e32 v101, v65
	v_or_b32_e32 v64, s11, v30
	v_or_b32_e32 v53, s11, v31
	v_lshlrev_b32_e32 v64, 10, v64
	v_lshlrev_b32_e32 v53, 10, v53
	v_or_b32_e32 v64, v52, v64
	v_or_b32_e32 v100, v52, v53
	v_lshl_add_u64 v[102:103], v[64:65], 2, s[4:5]
	v_lshl_add_u64 v[100:101], v[100:101], 2, s[4:5]
	global_load_dword v166, v[102:103], off
	global_load_dword v167, v[100:101], off
	v_mov_b32_e32 v101, v65
	v_or_b32_e32 v64, s11, v32
	v_or_b32_e32 v53, s11, v33
	v_lshlrev_b32_e32 v64, 10, v64
	v_lshlrev_b32_e32 v53, 10, v53
	v_or_b32_e32 v64, v52, v64
	v_or_b32_e32 v100, v52, v53
	v_lshl_add_u64 v[102:103], v[64:65], 2, s[4:5]
	v_lshl_add_u64 v[100:101], v[100:101], 2, s[4:5]
	global_load_dword v168, v[102:103], off
	global_load_dword v169, v[100:101], off
	v_mov_b32_e32 v101, v65
	v_or_b32_e32 v64, s11, v34
	v_or_b32_e32 v53, s11, v35
	v_lshlrev_b32_e32 v64, 10, v64
	v_lshlrev_b32_e32 v53, 10, v53
	v_or_b32_e32 v64, v52, v64
	v_or_b32_e32 v100, v52, v53
	v_lshl_add_u64 v[102:103], v[64:65], 2, s[4:5]
	v_lshl_add_u64 v[100:101], v[100:101], 2, s[4:5]
	global_load_dword v170, v[102:103], off
	global_load_dword v171, v[100:101], off
	v_mov_b32_e32 v101, v65
	v_or_b32_e32 v64, s11, v36
	v_or_b32_e32 v53, s11, v37
	v_lshlrev_b32_e32 v64, 10, v64
	v_lshlrev_b32_e32 v53, 10, v53
	v_or_b32_e32 v64, v52, v64
	v_or_b32_e32 v100, v52, v53
	v_lshl_add_u64 v[102:103], v[64:65], 2, s[4:5]
	v_lshl_add_u64 v[100:101], v[100:101], 2, s[4:5]
	global_load_dword v172, v[102:103], off
	global_load_dword v173, v[100:101], off
	v_mov_b32_e32 v101, v65
	v_or_b32_e32 v64, s11, v38
	v_or_b32_e32 v53, s11, v39
	v_lshlrev_b32_e32 v64, 10, v64
	v_lshlrev_b32_e32 v53, 10, v53
	v_or_b32_e32 v64, v52, v64
	v_or_b32_e32 v100, v52, v53
	v_lshl_add_u64 v[102:103], v[64:65], 2, s[4:5]
	v_lshl_add_u64 v[100:101], v[100:101], 2, s[4:5]
	global_load_dword v174, v[102:103], off
	global_load_dword v175, v[100:101], off
	v_mov_b32_e32 v101, v65
	v_or_b32_e32 v64, s11, v40
	v_or_b32_e32 v53, s11, v41
	v_lshlrev_b32_e32 v64, 10, v64
	v_lshlrev_b32_e32 v53, 10, v53
	v_or_b32_e32 v64, v52, v64
	v_or_b32_e32 v100, v52, v53
	v_lshl_add_u64 v[102:103], v[64:65], 2, s[4:5]
	v_lshl_add_u64 v[100:101], v[100:101], 2, s[4:5]
	global_load_dword v176, v[102:103], off
	global_load_dword v177, v[100:101], off
	v_mov_b32_e32 v101, v65
	v_or_b32_e32 v64, s11, v42
	v_or_b32_e32 v53, s11, v43
	v_lshlrev_b32_e32 v64, 10, v64
	v_lshlrev_b32_e32 v53, 10, v53
	v_or_b32_e32 v64, v52, v64
	v_or_b32_e32 v100, v52, v53
	v_lshl_add_u64 v[102:103], v[64:65], 2, s[4:5]
	v_lshl_add_u64 v[100:101], v[100:101], 2, s[4:5]
	global_load_dword v178, v[102:103], off
	global_load_dword v179, v[100:101], off
	v_mov_b32_e32 v101, v65
	v_or_b32_e32 v64, s11, v44
	v_or_b32_e32 v53, s11, v45
	v_lshlrev_b32_e32 v64, 10, v64
	v_lshlrev_b32_e32 v53, 10, v53
	v_or_b32_e32 v64, v52, v64
	v_or_b32_e32 v100, v52, v53
	v_lshl_add_u64 v[102:103], v[64:65], 2, s[4:5]
	v_lshl_add_u64 v[100:101], v[100:101], 2, s[4:5]
	global_load_dword v180, v[102:103], off
	global_load_dword v181, v[100:101], off
	v_mov_b32_e32 v101, v65
	v_or_b32_e32 v64, s11, v46
	v_or_b32_e32 v53, s11, v47
	v_lshlrev_b32_e32 v64, 10, v64
	v_lshlrev_b32_e32 v53, 10, v53
	v_or_b32_e32 v64, v52, v64
	v_or_b32_e32 v100, v52, v53
	v_lshl_add_u64 v[102:103], v[64:65], 2, s[4:5]
	v_lshl_add_u64 v[100:101], v[100:101], 2, s[4:5]
	global_load_dword v182, v[102:103], off
	global_load_dword v183, v[100:101], off
	v_mov_b32_e32 v101, v65
	v_or_b32_e32 v64, s11, v48
	v_or_b32_e32 v53, s11, v49
	v_lshlrev_b32_e32 v64, 10, v64
	v_lshlrev_b32_e32 v53, 10, v53
	v_or_b32_e32 v64, v52, v64
	v_or_b32_e32 v100, v52, v53
	v_lshl_add_u64 v[102:103], v[64:65], 2, s[4:5]
	v_lshl_add_u64 v[100:101], v[100:101], 2, s[4:5]
	global_load_dword v184, v[102:103], off
	global_load_dword v185, v[100:101], off
	v_mov_b32_e32 v101, v65
	v_or_b32_e32 v64, s11, v50
	v_or_b32_e32 v53, s11, v51
	v_lshlrev_b32_e32 v64, 10, v64
	v_lshlrev_b32_e32 v53, 10, v53
	v_or_b32_e32 v64, v52, v64
	v_or_b32_e32 v100, v52, v53
	v_lshl_add_u64 v[52:53], v[64:65], 2, s[4:5]
	v_lshl_add_u64 v[100:101], v[100:101], 2, s[4:5]
	global_load_dword v186, v[52:53], off
	s_nop 0
	global_load_dword v187, v[100:101], off
	s_mov_b32 s11, s19
	v_writelane_b32 v254, s10, 58
	s_waitcnt vmcnt(0)
; __device__ __forceinline__ unsigned cvt_pk_f16(float lo, float hi) { f32x2_t v = {lo, hi}; f16x2_t h = __builtin_convertvector(v, f16x2_t); return __builtin_bit_cast(unsigned, h); }
; #define LAS __attribute__((address_space(3)))
; __device__ __forceinline__ unsigned pk2(float lo, float hi) { return pg8::cvt_pk_bf16(lo, hi); }
; template <bool F16 = false> __device__ __forceinline__ void tr_item(const float* W, int N, bf16* WT, int ldk, int koff, int k0, int n0, int drow0, LAS float* scr, int lane) {
;     ...
;     for (int i = 0; i < 32; ++i) { const int kk = 2 * i + (lane >> 5); scr[kk * 33 + (lane & 31)] = W[(size_t)(k0 + kk) * N + n0 + (lane & 31)]; }
;     asm volatile("s_waitcnt lgkmcnt(0)" ::: "memory");
;     const int c = lane & 7;
; #pragma unroll
;     for (int j = 0; j < 4; ++j) { const int n = (lane >> 3) + 8 * j; const LAS float* s = scr + (8 * c) * 33 + n;
;         u32x4 o;
;         if constexpr (F16) { o.x = pg8::cvt_pk_f16(s[0 * 33], s[1 * 33]); o.y = pg8::cvt_pk_f16(s[2 * 33], s[3 * 33]); o.z = pg8::cvt_pk_f16(s[4 * 33], s[5 * 33]); o.w = pg8::cvt_pk_f16(s[6 * 33], s[7 * 33]); }
;         else { o.x = pk2(s[0 * 33], s[1 * 33]); o.y = pk2(s[2 * 33], s[3 * 33]); o.z = pk2(s[4 * 33], s[5 * 33]); o.w = pk2(s[6 * 33], s[7 * 33]); }
;         *(u32x4*)(WT + (size_t)(drow0 + n) * ldk + koff + k0 + 8 * c) = o; }
;     asm volatile("s_waitcnt lgkmcnt(0)" ::: "memory");
	v_add_u32_e32 v99, v56, v67
	ds_write_b32 v99, v156
	v_add_u32_e32 v53, v56, v68
	ds_write_b32 v53, v157
	v_add_u32_e32 v99, v56, v69
	ds_write_b32 v99, v158
	v_add_u32_e32 v53, v56, v70
	ds_write_b32 v53, v159
	v_add_u32_e32 v99, v56, v71
	ds_write_b32 v99, v160
	v_add_u32_e32 v53, v56, v72
	ds_write_b32 v53, v161
	v_add_u32_e32 v99, v56, v73
	ds_write_b32 v99, v162
	v_add_u32_e32 v53, v56, v74
	ds_write_b32 v53, v163
	v_add_u32_e32 v99, v56, v75
	ds_write_b32 v99, v164
	v_add_u32_e32 v53, v56, v76
	ds_write_b32 v53, v165
	v_add_u32_e32 v99, v56, v77
	ds_write_b32 v99, v166
	v_add_u32_e32 v53, v56, v78
	ds_write_b32 v53, v167
	v_add_u32_e32 v99, v56, v79
	ds_write_b32 v99, v168
	v_add_u32_e32 v53, v56, v80
	ds_write_b32 v53, v169
	v_add_u32_e32 v99, v56, v81
	ds_write_b32 v99, v170
	v_add_u32_e32 v53, v56, v82
	ds_write_b32 v53, v171
	v_add_u32_e32 v99, v56, v83
	ds_write_b32 v99, v172
	v_add_u32_e32 v53, v56, v84
	ds_write_b32 v53, v173
	v_add_u32_e32 v99, v56, v85
	ds_write_b32 v99, v174
	v_add_u32_e32 v53, v56, v86
	ds_write_b32 v53, v175
	v_add_u32_e32 v99, v56, v87
	ds_write_b32 v99, v176
	v_add_u32_e32 v53, v56, v88
	ds_write_b32 v53, v177
	v_add_u32_e32 v99, v56, v89
	ds_write_b32 v99, v178
	v_add_u32_e32 v53, v56, v90
	ds_write_b32 v53, v179
	v_add_u32_e32 v99, v56, v91
	ds_write_b32 v99, v180
	v_add_u32_e32 v53, v56, v92
	ds_write_b32 v53, v181
	v_add_u32_e32 v99, v56, v93
	ds_write_b32 v99, v182
	v_add_u32_e32 v53, v56, v94
	ds_write_b32 v53, v183
	v_add_u32_e32 v99, v56, v95
	ds_write_b32 v99, v184
	v_add_u32_e32 v53, v56, v96
	ds_write_b32 v53, v185
	v_add_u32_e32 v64, v56, v97
	ds_write_b32 v64, v186
	v_add_u32_e32 v52, v56, v98
	ds_write_b32 v52, v187
	s_waitcnt lgkmcnt(0)
	ds_read2_b32 v[104:105], v58 offset0:33 offset1:41
	ds_read2_b32 v[106:107], v58 offset1:8
	ds_read2_b32 v[108:109], v58 offset0:66 offset1:74
	ds_read2_b32 v[110:111], v58 offset0:99 offset1:107
	ds_read2_b32 v[112:113], v58 offset0:132 offset1:140
	ds_read2_b32 v[114:115], v58 offset0:165 offset1:173
	ds_read2_b32 v[116:117], v58 offset0:198 offset1:206
	ds_read2_b32 v[118:119], v58 offset0:231 offset1:239
	v_or_b32_e32 v64, s10, v57
	v_lshl_add_u64 v[52:53], v[12:13], 0, s[18:19]
	v_lshlrev_b32_e32 v64, 12, v64
	v_lshl_add_u64 v[120:121], v[52:53], 0, v[64:65]
	v_or_b32_e32 v64, s10, v59
	s_waitcnt lgkmcnt(6)
	v_cvt_pk_bf16_f32 v100, v106, v104
	s_waitcnt lgkmcnt(4)
	v_cvt_pk_bf16_f32 v101, v108, v110
	s_waitcnt lgkmcnt(2)
	v_cvt_pk_bf16_f32 v102, v112, v114
	s_waitcnt lgkmcnt(0)
	v_cvt_pk_bf16_f32 v103, v116, v118
	v_lshlrev_b32_e32 v64, 12, v64
	global_store_dwordx4 v[120:121], v[100:103], off
	v_writelane_b32 v254, s11, 59
	s_nop 0
	v_cvt_pk_bf16_f32 v100, v107, v105
	v_cvt_pk_bf16_f32 v101, v109, v111
	v_cvt_pk_bf16_f32 v102, v113, v115
	v_cvt_pk_bf16_f32 v103, v117, v119
	v_lshl_add_u64 v[104:105], v[52:53], 0, v[64:65]
	global_store_dwordx4 v[104:105], v[100:103], off
	ds_read2_b32 v[104:105], v58 offset0:49 offset1:57
	ds_read2_b32 v[106:107], v58 offset0:16 offset1:24
	ds_read2_b32 v[108:109], v58 offset0:82 offset1:90
	ds_read2_b32 v[110:111], v58 offset0:115 offset1:123
	ds_read2_b32 v[112:113], v58 offset0:148 offset1:156
	ds_read2_b32 v[114:115], v58 offset0:181 offset1:189
	ds_read2_b32 v[116:117], v58 offset0:214 offset1:222
	ds_read2_b32 v[118:119], v58 offset0:247 offset1:255
	v_or_b32_e32 v64, s10, v60
	v_lshlrev_b32_e32 v64, 12, v64
	v_lshl_add_u64 v[120:121], v[52:53], 0, v[64:65]
	v_or_b32_e32 v64, s10, v61
	s_waitcnt lgkmcnt(6)
	v_cvt_pk_bf16_f32 v100, v106, v104
	s_waitcnt lgkmcnt(4)
	v_cvt_pk_bf16_f32 v101, v108, v110
	s_waitcnt lgkmcnt(2)
	v_cvt_pk_bf16_f32 v102, v112, v114
	s_waitcnt lgkmcnt(0)
	v_cvt_pk_bf16_f32 v103, v116, v118
	v_lshlrev_b32_e32 v64, 12, v64
	global_store_dwordx4 v[120:121], v[100:103], off
	v_lshl_add_u64 v[52:53], v[52:53], 0, v[64:65]
	s_nop 0
	v_cvt_pk_bf16_f32 v100, v107, v105
	v_cvt_pk_bf16_f32 v101, v109, v111
	v_cvt_pk_bf16_f32 v102, v113, v115
	v_cvt_pk_bf16_f32 v103, v117, v119
	global_store_dwordx4 v[52:53], v[100:103], off
	s_waitcnt lgkmcnt(0)

; #define LAS __attribute__((address_space(3)))
; template <bool F16 = false> __device__ __forceinline__ void tr_item(const float* W, int N, bf16* WT, int ldk, int koff, int k0, int n0, int drow0, LAS float* scr, int lane) {
; #pragma unroll 16
;     for (int i = 0; i < 32; ++i) { const int kk = 2 * i + (lane >> 5); scr[kk * 33 + (lane & 31)] = W[(size_t)(k0 + kk) * N + n0 + (lane & 31)]; }
; __device__ __forceinline__ void convert_layer(const Args& a, int l, LAS unsigned char* lds, int gw, int NGW, int lane, int wave, bool gates = true) {
;     ...
;         if (r < I_SQ) { tr_item(w_pa, DM, (bf16*)(ws + WS_W2), 2048, 0, 64 * (r >> 5), 32 * (r & 31), 32 * (r & 31), scr, lane); continue; } r -= I_SQ;
.LBB0_625:
	s_andn2_b64 vcc, exec, s[18:19]
	s_cbranch_vccnz .LBB0_627
	s_add_i32 s10, s37, 0x1000
	s_and_b32 s11, s10, 0x7fffffc0
	s_and_b32 s10, s31, 0x3e0
	v_or_b32_e32 v52, s11, v1
	v_or_b32_e32 v53, s11, v0
	v_lshlrev_b32_e32 v64, 10, v52
	v_lshlrev_b32_e32 v53, 10, v53
	v_or_b32_e32 v52, s10, v55
	v_or_b32_e32 v100, v52, v64
	v_or_b32_e32 v64, v52, v53
	v_lshl_add_u64 v[102:103], v[64:65], 2, s[2:3]
	v_mov_b32_e32 v101, v65
	v_lshl_add_u64 v[100:101], v[100:101], 2, s[2:3]
	global_load_dword v156, v[102:103], off
	global_load_dword v157, v[100:101], off
	v_mov_b32_e32 v101, v65
	v_readlane_b32 s18, v254, 58
	v_readlane_b32 s19, v254, 59
	s_lshl_b32 s18, s11, 1
	v_or_b32_e32 v64, s11, v22
	v_or_b32_e32 v53, s11, v23
	v_lshlrev_b32_e32 v64, 10, v64
	v_lshlrev_b32_e32 v53, 10, v53
	v_or_b32_e32 v64, v52, v64
	v_or_b32_e32 v100, v52, v53
	v_lshl_add_u64 v[102:103], v[64:65], 2, s[2:3]
	v_lshl_add_u64 v[100:101], v[100:101], 2, s[2:3]
	global_load_dword v158, v[102:103], off
	global_load_dword v159, v[100:101], off
	v_mov_b32_e32 v101, v65
	v_or_b32_e32 v64, s11, v24
	v_or_b32_e32 v53, s11, v25
	v_lshlrev_b32_e32 v64, 10, v64
	v_lshlrev_b32_e32 v53, 10, v53
	v_or_b32_e32 v64, v52, v64
	v_or_b32_e32 v100, v52, v53
	v_lshl_add_u64 v[102:103], v[64:65], 2, s[2:3]
	v_lshl_add_u64 v[100:101], v[100:101], 2, s[2:3]
	global_load_dword v160, v[102:103], off
	global_load_dword v161, v[100:101], off
	v_mov_b32_e32 v101, v65
	v_or_b32_e32 v64, s11, v26
	v_or_b32_e32 v53, s11, v27
	v_lshlrev_b32_e32 v64, 10, v64
	v_lshlrev_b32_e32 v53, 10, v53
	v_or_b32_e32 v64, v52, v64
	v_or_b32_e32 v100, v52, v53
	v_lshl_add_u64 v[102:103], v[64:65], 2, s[2:3]
	v_lshl_add_u64 v[100:101], v[100:101], 2, s[2:3]
	global_load_dword v162, v[102:103], off
	global_load_dword v163, v[100:101], off
	v_mov_b32_e32 v101, v65
	v_or_b32_e32 v64, s11, v28
	v_or_b32_e32 v53, s11, v29
	v_lshlrev_b32_e32 v64, 10, v64
	v_lshlrev_b32_e32 v53, 10, v53
	v_or_b32_e32 v64, v52, v64
	v_or_b32_e32 v100, v52, v53
	v_lshl_add_u64 v[102:103], v[64:65], 2, s[2:3]
	v_lshl_add_u64 v[100:101], v[100:101], 2, s[2:3]
	global_load_dword v164, v[102:103], off
	global_load_dword v165, v[100:101], off
	v_mov_b32_e32 v101, v65
	v_or_b32_e32 v64, s11, v30
	v_or_b32_e32 v53, s11, v31
	v_lshlrev_b32_e32 v64, 10, v64
	v_lshlrev_b32_e32 v53, 10, v53
	v_or_b32_e32 v64, v52, v64
	v_or_b32_e32 v100, v52, v53
	v_lshl_add_u64 v[102:103], v[64:65], 2, s[2:3]
	v_lshl_add_u64 v[100:101], v[100:101], 2, s[2:3]
	global_load_dword v166, v[102:103], off
	global_load_dword v167, v[100:101], off
	v_mov_b32_e32 v101, v65
	v_or_b32_e32 v64, s11, v32
	v_or_b32_e32 v53, s11, v33
	v_lshlrev_b32_e32 v64, 10, v64
	v_lshlrev_b32_e32 v53, 10, v53
	v_or_b32_e32 v64, v52, v64
	v_or_b32_e32 v100, v52, v53
	v_lshl_add_u64 v[102:103], v[64:65], 2, s[2:3]
	v_lshl_add_u64 v[100:101], v[100:101], 2, s[2:3]
	global_load_dword v168, v[102:103], off
	global_load_dword v169, v[100:101], off
	v_mov_b32_e32 v101, v65
	v_or_b32_e32 v64, s11, v34
	v_or_b32_e32 v53, s11, v35
	v_lshlrev_b32_e32 v64, 10, v64
	v_lshlrev_b32_e32 v53, 10, v53
	v_or_b32_e32 v64, v52, v64
	v_or_b32_e32 v100, v52, v53
	v_lshl_add_u64 v[102:103], v[64:65], 2, s[2:3]
	v_lshl_add_u64 v[100:101], v[100:101], 2, s[2:3]
	global_load_dword v170, v[102:103], off
	global_load_dword v171, v[100:101], off
	v_mov_b32_e32 v101, v65
	v_or_b32_e32 v64, s11, v36
	v_or_b32_e32 v53, s11, v37
	v_lshlrev_b32_e32 v64, 10, v64
	v_lshlrev_b32_e32 v53, 10, v53
	v_or_b32_e32 v64, v52, v64
	v_or_b32_e32 v100, v52, v53
	v_lshl_add_u64 v[102:103], v[64:65], 2, s[2:3]
	v_lshl_add_u64 v[100:101], v[100:101], 2, s[2:3]
	global_load_dword v172, v[102:103], off
	global_load_dword v173, v[100:101], off
	v_mov_b32_e32 v101, v65
	v_or_b32_e32 v64, s11, v38
	v_or_b32_e32 v53, s11, v39
	v_lshlrev_b32_e32 v64, 10, v64
	v_lshlrev_b32_e32 v53, 10, v53
	v_or_b32_e32 v64, v52, v64
	v_or_b32_e32 v100, v52, v53
	v_lshl_add_u64 v[102:103], v[64:65], 2, s[2:3]
	v_lshl_add_u64 v[100:101], v[100:101], 2, s[2:3]
	global_load_dword v174, v[102:103], off
	global_load_dword v175, v[100:101], off
	v_mov_b32_e32 v101, v65
	v_or_b32_e32 v64, s11, v40
	v_or_b32_e32 v53, s11, v41
	v_lshlrev_b32_e32 v64, 10, v64
	v_lshlrev_b32_e32 v53, 10, v53
	v_or_b32_e32 v64, v52, v64
	v_or_b32_e32 v100, v52, v53
	v_lshl_add_u64 v[102:103], v[64:65], 2, s[2:3]
	v_lshl_add_u64 v[100:101], v[100:101], 2, s[2:3]
	global_load_dword v176, v[102:103], off
	global_load_dword v177, v[100:101], off
	v_mov_b32_e32 v101, v65
	v_or_b32_e32 v64, s11, v42
	v_or_b32_e32 v53, s11, v43
	v_lshlrev_b32_e32 v64, 10, v64
	v_lshlrev_b32_e32 v53, 10, v53
	v_or_b32_e32 v64, v52, v64
	v_or_b32_e32 v100, v52, v53
	v_lshl_add_u64 v[102:103], v[64:65], 2, s[2:3]
	v_lshl_add_u64 v[100:101], v[100:101], 2, s[2:3]
	global_load_dword v178, v[102:103], off
	global_load_dword v179, v[100:101], off
	v_mov_b32_e32 v101, v65
	v_or_b32_e32 v64, s11, v44
	v_or_b32_e32 v53, s11, v45
	v_lshlrev_b32_e32 v64, 10, v64
	v_lshlrev_b32_e32 v53, 10, v53
	v_or_b32_e32 v64, v52, v64
	v_or_b32_e32 v100, v52, v53
	v_lshl_add_u64 v[102:103], v[64:65], 2, s[2:3]
	v_lshl_add_u64 v[100:101], v[100:101], 2, s[2:3]
	global_load_dword v180, v[102:103], off
	global_load_dword v181, v[100:101], off
	v_mov_b32_e32 v101, v65
	v_or_b32_e32 v64, s11, v46
	v_or_b32_e32 v53, s11, v47
	v_lshlrev_b32_e32 v64, 10, v64
	v_lshlrev_b32_e32 v53, 10, v53
	v_or_b32_e32 v64, v52, v64
	v_or_b32_e32 v100, v52, v53
	v_lshl_add_u64 v[102:103], v[64:65], 2, s[2:3]
	v_lshl_add_u64 v[100:101], v[100:101], 2, s[2:3]
	global_load_dword v182, v[102:103], off
	global_load_dword v183, v[100:101], off
	v_mov_b32_e32 v101, v65
	v_or_b32_e32 v64, s11, v48
	v_or_b32_e32 v53, s11, v49
	v_lshlrev_b32_e32 v64, 10, v64
	v_lshlrev_b32_e32 v53, 10, v53
	v_or_b32_e32 v64, v52, v64
	v_or_b32_e32 v100, v52, v53
	v_lshl_add_u64 v[102:103], v[64:65], 2, s[2:3]
	v_lshl_add_u64 v[100:101], v[100:101], 2, s[2:3]
	global_load_dword v184, v[102:103], off
	global_load_dword v185, v[100:101], off
	v_mov_b32_e32 v101, v65
	v_or_b32_e32 v64, s11, v50
	v_or_b32_e32 v53, s11, v51
	v_lshlrev_b32_e32 v64, 10, v64
	v_lshlrev_b32_e32 v53, 10, v53
	v_or_b32_e32 v64, v52, v64
	v_or_b32_e32 v100, v52, v53
	v_lshl_add_u64 v[52:53], v[64:65], 2, s[2:3]
	v_lshl_add_u64 v[100:101], v[100:101], 2, s[2:3]
	global_load_dword v186, v[52:53], off
	s_nop 0
	global_load_dword v187, v[100:101], off
	s_mov_b32 s11, s19
	v_writelane_b32 v254, s10, 58
	s_waitcnt vmcnt(0)
; __device__ __forceinline__ unsigned cvt_pk_f16(float lo, float hi) { f32x2_t v = {lo, hi}; f16x2_t h = __builtin_convertvector(v, f16x2_t); return __builtin_bit_cast(unsigned, h); }
; #define LAS __attribute__((address_space(3)))
; __device__ __forceinline__ unsigned pk2(float lo, float hi) { return pg8::cvt_pk_bf16(lo, hi); }
; template <bool F16 = false> __device__ __forceinline__ void tr_item(const float* W, int N, bf16* WT, int ldk, int koff, int k0, int n0, int drow0, LAS float* scr, int lane) {
;     ...
;     for (int i = 0; i < 32; ++i) { const int kk = 2 * i + (lane >> 5); scr[kk * 33 + (lane & 31)] = W[(size_t)(k0 + kk) * N + n0 + (lane & 31)]; }
;     asm volatile("s_waitcnt lgkmcnt(0)" ::: "memory");
;     const int c = lane & 7;
; #pragma unroll
;     for (int j = 0; j < 4; ++j) { const int n = (lane >> 3) + 8 * j; const LAS float* s = scr + (8 * c) * 33 + n;
;         u32x4 o;
;         if constexpr (F16) { o.x = pg8::cvt_pk_f16(s[0 * 33], s[1 * 33]); o.y = pg8::cvt_pk_f16(s[2 * 33], s[3 * 33]); o.z = pg8::cvt_pk_f16(s[4 * 33], s[5 * 33]); o.w = pg8::cvt_pk_f16(s[6 * 33], s[7 * 33]); }
;         else { o.x = pk2(s[0 * 33], s[1 * 33]); o.y = pk2(s[2 * 33], s[3 * 33]); o.z = pk2(s[4 * 33], s[5 * 33]); o.w = pk2(s[6 * 33], s[7 * 33]); }
;         *(u32x4*)(WT + (size_t)(drow0 + n) * ldk + koff + k0 + 8 * c) = o; }
;     asm volatile("s_waitcnt lgkmcnt(0)" ::: "memory");
	v_add_u32_e32 v99, v56, v67
	ds_write_b32 v99, v156
	v_add_u32_e32 v53, v56, v68
	ds_write_b32 v53, v157
	v_add_u32_e32 v99, v56, v69
	ds_write_b32 v99, v158
	v_add_u32_e32 v53, v56, v70
	ds_write_b32 v53, v159
	v_add_u32_e32 v99, v56, v71
	ds_write_b32 v99, v160
	v_add_u32_e32 v53, v56, v72
	ds_write_b32 v53, v161
	v_add_u32_e32 v99, v56, v73
	ds_write_b32 v99, v162
	v_add_u32_e32 v53, v56, v74
	ds_write_b32 v53, v163
	v_add_u32_e32 v99, v56, v75
	ds_write_b32 v99, v164
	v_add_u32_e32 v53, v56, v76
	ds_write_b32 v53, v165
	v_add_u32_e32 v99, v56, v77
	ds_write_b32 v99, v166
	v_add_u32_e32 v53, v56, v78
	ds_write_b32 v53, v167
	v_add_u32_e32 v99, v56, v79
	ds_write_b32 v99, v168
	v_add_u32_e32 v53, v56, v80
	ds_write_b32 v53, v169
	v_add_u32_e32 v99, v56, v81
	ds_write_b32 v99, v170
	v_add_u32_e32 v53, v56, v82
	ds_write_b32 v53, v171
	v_add_u32_e32 v99, v56, v83
	ds_write_b32 v99, v172
	v_add_u32_e32 v53, v56, v84
	ds_write_b32 v53, v173
	v_add_u32_e32 v99, v56, v85
	ds_write_b32 v99, v174
	v_add_u32_e32 v53, v56, v86
	ds_write_b32 v53, v175
	v_add_u32_e32 v99, v56, v87
	ds_write_b32 v99, v176
	v_add_u32_e32 v53, v56, v88
	ds_write_b32 v53, v177
	v_add_u32_e32 v99, v56, v89
	ds_write_b32 v99, v178
	v_add_u32_e32 v53, v56, v90
	ds_write_b32 v53, v179
	v_add_u32_e32 v99, v56, v91
	ds_write_b32 v99, v180
	v_add_u32_e32 v53, v56, v92
	ds_write_b32 v53, v181
	v_add_u32_e32 v99, v56, v93
	ds_write_b32 v99, v182
	v_add_u32_e32 v53, v56, v94
	ds_write_b32 v53, v183
	v_add_u32_e32 v99, v56, v95
	ds_write_b32 v99, v184
	v_add_u32_e32 v53, v56, v96
	ds_write_b32 v53, v185
	v_add_u32_e32 v64, v56, v97
	ds_write_b32 v64, v186
	v_add_u32_e32 v52, v56, v98
	ds_write_b32 v52, v187
	s_waitcnt lgkmcnt(0)
	ds_read2_b32 v[104:105], v58 offset0:33 offset1:41
	ds_read2_b32 v[106:107], v58 offset1:8
	ds_read2_b32 v[108:109], v58 offset0:66 offset1:74
	ds_read2_b32 v[110:111], v58 offset0:99 offset1:107
	ds_read2_b32 v[112:113], v58 offset0:132 offset1:140
	ds_read2_b32 v[114:115], v58 offset0:165 offset1:173
	ds_read2_b32 v[116:117], v58 offset0:198 offset1:206
	ds_read2_b32 v[118:119], v58 offset0:231 offset1:239
	v_or_b32_e32 v64, s10, v57
	v_lshl_add_u64 v[52:53], v[14:15], 0, s[18:19]
	v_lshlrev_b32_e32 v64, 12, v64
	v_lshl_add_u64 v[120:121], v[52:53], 0, v[64:65]
	v_or_b32_e32 v64, s10, v59
	s_waitcnt lgkmcnt(6)
	v_cvt_pk_bf16_f32 v100, v106, v104
	s_waitcnt lgkmcnt(4)
	v_cvt_pk_bf16_f32 v101, v108, v110
	s_waitcnt lgkmcnt(2)
	v_cvt_pk_bf16_f32 v102, v112, v114
	s_waitcnt lgkmcnt(0)
	v_cvt_pk_bf16_f32 v103, v116, v118
	v_lshlrev_b32_e32 v64, 12, v64
	global_store_dwordx4 v[120:121], v[100:103], off
	v_writelane_b32 v254, s11, 59
	s_nop 0
	v_cvt_pk_bf16_f32 v100, v107, v105
	v_cvt_pk_bf16_f32 v101, v109, v111
	v_cvt_pk_bf16_f32 v102, v113, v115
	v_cvt_pk_bf16_f32 v103, v117, v119
	v_lshl_add_u64 v[104:105], v[52:53], 0, v[64:65]
	global_store_dwordx4 v[104:105], v[100:103], off
	ds_read2_b32 v[104:105], v58 offset0:49 offset1:57
	ds_read2_b32 v[106:107], v58 offset0:16 offset1:24
	ds_read2_b32 v[108:109], v58 offset0:82 offset1:90
	ds_read2_b32 v[110:111], v58 offset0:115 offset1:123
	ds_read2_b32 v[112:113], v58 offset0:148 offset1:156
	ds_read2_b32 v[114:115], v58 offset0:181 offset1:189
	ds_read2_b32 v[116:117], v58 offset0:214 offset1:222
	ds_read2_b32 v[118:119], v58 offset0:247 offset1:255
	v_or_b32_e32 v64, s10, v60
	v_lshlrev_b32_e32 v64, 12, v64
	v_lshl_add_u64 v[120:121], v[52:53], 0, v[64:65]
	v_or_b32_e32 v64, s10, v61
	s_waitcnt lgkmcnt(6)
	v_cvt_pk_bf16_f32 v100, v106, v104
	s_waitcnt lgkmcnt(4)
	v_cvt_pk_bf16_f32 v101, v108, v110
	s_waitcnt lgkmcnt(2)
	v_cvt_pk_bf16_f32 v102, v112, v114
	s_waitcnt lgkmcnt(0)
	v_cvt_pk_bf16_f32 v103, v116, v118
	v_lshlrev_b32_e32 v64, 12, v64
	global_store_dwordx4 v[120:121], v[100:103], off
	v_lshl_add_u64 v[52:53], v[52:53], 0, v[64:65]
	s_nop 0
	v_cvt_pk_bf16_f32 v100, v107, v105
	v_cvt_pk_bf16_f32 v101, v109, v111
	v_cvt_pk_bf16_f32 v102, v113, v115
	v_cvt_pk_bf16_f32 v103, v117, v119
	global_store_dwordx4 v[52:53], v[100:103], off
	s_waitcnt lgkmcnt(0)

; #define LAS __attribute__((address_space(3)))
; template <bool F16 = false> __device__ __forceinline__ void tr_item(const float* W, int N, bf16* WT, int ldk, int koff, int k0, int n0, int drow0, LAS float* scr, int lane) {
; #pragma unroll 16
;     for (int i = 0; i < 32; ++i) { const int kk = 2 * i + (lane >> 5); scr[kk * 33 + (lane & 31)] = W[(size_t)(k0 + kk) * N + n0 + (lane & 31)]; }
; __device__ __forceinline__ void win_item(const Args& a, int l, unsigned char* wb, int kb, int nb, int what, LAS float* scr, int lane) {
;     const float* w_in = a.in[2] + (size_t)l * DM * NIN; const int drow0 = win_dest_row(32 * nb);
;     if (drow0 >= 7168) { if (what >= 1) tr_item_q(w_in, (const float*)(a.ws + WS_CMAX) + l * 2048, wb + WS_WIN + (size_t)7168 * 2048, 64 * kb, 32 * nb, drow0 - 7168, scr, lane); return; }
;     const int slot = pg8::p1_qslot(drow0 >> 8);
;     if (slot >= 0) { if (what >= 1) tr_item_q(w_in, (const float*)(a.ws + WS_CMAX1) + l * (pg8::P1_NQ * 256), wb + WS_WIN, 64 * kb, 32 * nb, slot * 256 + (drow0 & 255), scr, lane); return; }
;     if (what != 1) tr_item<true>(w_in, NIN, (bf16*)(wb + WS_WIN), 1024, 0, 64 * kb, 32 * nb, drow0, scr, lane);
.LBB0_645:
	s_lshl_b32 s22, s11, 6
	s_ashr_i32 s19, s18, 31
	s_cmp_gt_i32 s10, -1
	v_lshl_add_u64 v[52:53], s[18:19], 2, v[20:21]
	s_mov_b64 s[28:29], -1
	v_or_b32_e32 v128, s22, v1
	v_or_b32_e32 v129, s22, v0
	v_or_b32_e32 v126, s22, v23
	v_or_b32_e32 v127, s22, v22
	v_or_b32_e32 v124, s22, v25
	v_or_b32_e32 v125, s22, v24
	v_or_b32_e32 v122, s22, v27
	v_or_b32_e32 v123, s22, v26
	v_or_b32_e32 v120, s22, v29
	v_or_b32_e32 v121, s22, v28
	v_or_b32_e32 v118, s22, v31
	v_or_b32_e32 v119, s22, v30
	v_or_b32_e32 v116, s22, v33
	v_or_b32_e32 v117, s22, v32
	v_or_b32_e32 v114, s22, v35
	v_or_b32_e32 v115, s22, v34
	v_or_b32_e32 v112, s22, v37
	v_or_b32_e32 v113, s22, v36
	v_or_b32_e32 v110, s22, v39
	v_or_b32_e32 v111, s22, v38
	v_or_b32_e32 v108, s22, v41
	v_or_b32_e32 v109, s22, v40
	v_or_b32_e32 v106, s22, v43
	v_or_b32_e32 v107, s22, v42
	v_or_b32_e32 v104, s22, v45
	v_or_b32_e32 v105, s22, v44
	v_or_b32_e32 v102, s22, v47
	v_or_b32_e32 v103, s22, v46
	v_or_b32_e32 v100, s22, v49
	v_or_b32_e32 v101, s22, v48
	v_or_b32_e32 v64, s22, v51
	v_or_b32_e32 v99, s22, v50
	s_cbranch_scc1 .LBB0_647
	s_mov_b32 s19, 0x9000
	v_mad_i64_i32 v[130:131], s[20:21], v129, s19, v[52:53]
	v_mad_i64_i32 v[132:133], s[20:21], v128, s19, v[52:53]
	global_load_dword v156, v[130:131], off
	s_nop 0
	global_load_dword v157, v[132:133], off
	v_add_u32_e32 v152, s10, v57
	s_ashr_i32 s23, s22, 31
	v_ashrrev_i32_e32 v153, 31, v152
	v_lshl_add_u64 v[134:135], s[22:23], 1, v[2:3]
	v_lshlrev_b64 v[152:153], 11, v[152:153]
	v_lshl_add_u64 v[152:153], v[134:135], 0, v[152:153]
	s_mov_b64 s[28:29], 0
	v_mad_i64_i32 v[130:131], s[20:21], v127, s19, v[52:53]
	v_mad_i64_i32 v[132:133], s[20:21], v126, s19, v[52:53]
	global_load_dword v158, v[130:131], off
	s_nop 0
	global_load_dword v159, v[132:133], off
	v_mad_i64_i32 v[130:131], s[20:21], v125, s19, v[52:53]
	v_mad_i64_i32 v[132:133], s[20:21], v124, s19, v[52:53]
	global_load_dword v160, v[130:131], off
	s_nop 0
	global_load_dword v161, v[132:133], off
	v_mad_i64_i32 v[130:131], s[20:21], v123, s19, v[52:53]
	v_mad_i64_i32 v[132:133], s[20:21], v122, s19, v[52:53]
	global_load_dword v162, v[130:131], off
	s_nop 0
	global_load_dword v163, v[132:133], off
	v_mad_i64_i32 v[130:131], s[20:21], v121, s19, v[52:53]
	v_mad_i64_i32 v[132:133], s[20:21], v120, s19, v[52:53]
	global_load_dword v164, v[130:131], off
	s_nop 0
	global_load_dword v165, v[132:133], off
	v_mad_i64_i32 v[130:131], s[20:21], v119, s19, v[52:53]
	v_mad_i64_i32 v[132:133], s[20:21], v118, s19, v[52:53]
	global_load_dword v166, v[130:131], off
	s_nop 0
	global_load_dword v167, v[132:133], off
	v_mad_i64_i32 v[130:131], s[20:21], v117, s19, v[52:53]
	v_mad_i64_i32 v[132:133], s[20:21], v116, s19, v[52:53]
	global_load_dword v168, v[130:131], off
	s_nop 0
	global_load_dword v169, v[132:133], off
	v_mad_i64_i32 v[130:131], s[20:21], v115, s19, v[52:53]
	v_mad_i64_i32 v[132:133], s[20:21], v114, s19, v[52:53]
	global_load_dword v170, v[130:131], off
	s_nop 0
	global_load_dword v171, v[132:133], off
	v_mad_i64_i32 v[130:131], s[20:21], v113, s19, v[52:53]
	v_mad_i64_i32 v[132:133], s[20:21], v112, s19, v[52:53]
	global_load_dword v172, v[130:131], off
	s_nop 0
	global_load_dword v173, v[132:133], off
	v_mad_i64_i32 v[130:131], s[20:21], v111, s19, v[52:53]
	v_mad_i64_i32 v[132:133], s[20:21], v110, s19, v[52:53]
	global_load_dword v174, v[130:131], off
	s_nop 0
	global_load_dword v175, v[132:133], off
	v_mad_i64_i32 v[130:131], s[20:21], v109, s19, v[52:53]
	v_mad_i64_i32 v[132:133], s[20:21], v108, s19, v[52:53]
	global_load_dword v176, v[130:131], off
	s_nop 0
	global_load_dword v177, v[132:133], off
	v_mad_i64_i32 v[130:131], s[20:21], v107, s19, v[52:53]
	v_mad_i64_i32 v[132:133], s[20:21], v106, s19, v[52:53]
	global_load_dword v178, v[130:131], off
	s_nop 0
	global_load_dword v179, v[132:133], off
	v_mad_i64_i32 v[130:131], s[20:21], v105, s19, v[52:53]
	v_mad_i64_i32 v[132:133], s[20:21], v104, s19, v[52:53]
	global_load_dword v180, v[130:131], off
	s_nop 0
	global_load_dword v181, v[132:133], off
	v_mad_i64_i32 v[130:131], s[20:21], v103, s19, v[52:53]
	v_mad_i64_i32 v[132:133], s[20:21], v102, s19, v[52:53]
	global_load_dword v182, v[130:131], off
	s_nop 0
	global_load_dword v183, v[132:133], off
	v_mad_i64_i32 v[130:131], s[20:21], v101, s19, v[52:53]
	v_mad_i64_i32 v[132:133], s[20:21], v100, s19, v[52:53]
	global_load_dword v184, v[130:131], off
	s_nop 0
	global_load_dword v185, v[132:133], off
	v_mad_i64_i32 v[130:131], s[20:21], v99, s19, v[52:53]
	v_mad_i64_i32 v[132:133], s[20:21], v64, s19, v[52:53]
	global_load_dword v186, v[130:131], off
	s_nop 0
	global_load_dword v187, v[132:133], off
	s_waitcnt vmcnt(0)
; __device__ __forceinline__ unsigned cvt_pk_f16(float lo, float hi) { f32x2_t v = {lo, hi}; f16x2_t h = __builtin_convertvector(v, f16x2_t); return __builtin_bit_cast(unsigned, h); }
; #define LAS __attribute__((address_space(3)))
; __device__ __forceinline__ unsigned pk2(float lo, float hi) { return pg8::cvt_pk_bf16(lo, hi); }
; template <bool F16 = false> __device__ __forceinline__ void tr_item(const float* W, int N, bf16* WT, int ldk, int koff, int k0, int n0, int drow0, LAS float* scr, int lane) {
;     ...
;     for (int i = 0; i < 32; ++i) { const int kk = 2 * i + (lane >> 5); scr[kk * 33 + (lane & 31)] = W[(size_t)(k0 + kk) * N + n0 + (lane & 31)]; }
;     asm volatile("s_waitcnt lgkmcnt(0)" ::: "memory");
;     const int c = lane & 7;
; #pragma unroll
;     for (int j = 0; j < 4; ++j) { const int n = (lane >> 3) + 8 * j; const LAS float* s = scr + (8 * c) * 33 + n;
;         u32x4 o;
;         if constexpr (F16) { o.x = pg8::cvt_pk_f16(s[0 * 33], s[1 * 33]); o.y = pg8::cvt_pk_f16(s[2 * 33], s[3 * 33]); o.z = pg8::cvt_pk_f16(s[4 * 33], s[5 * 33]); o.w = pg8::cvt_pk_f16(s[6 * 33], s[7 * 33]); }
;         else { o.x = pk2(s[0 * 33], s[1 * 33]); o.y = pk2(s[2 * 33], s[3 * 33]); o.z = pk2(s[4 * 33], s[5 * 33]); o.w = pk2(s[6 * 33], s[7 * 33]); }
;         *(u32x4*)(WT + (size_t)(drow0 + n) * ldk + koff + k0 + 8 * c) = o; }
;     asm volatile("s_waitcnt lgkmcnt(0)" ::: "memory");
	v_add_u32_e32 v132, v56, v67
	ds_write_b32 v132, v156
	v_add_u32_e32 v130, v56, v68
	ds_write_b32 v130, v157
	v_add_u32_e32 v132, v56, v69
	ds_write_b32 v132, v158
	v_add_u32_e32 v130, v56, v70
	ds_write_b32 v130, v159
	v_add_u32_e32 v132, v56, v71
	ds_write_b32 v132, v160
	v_add_u32_e32 v130, v56, v72
	ds_write_b32 v130, v161
	v_add_u32_e32 v132, v56, v73
	ds_write_b32 v132, v162
	v_add_u32_e32 v130, v56, v74
	ds_write_b32 v130, v163
	v_add_u32_e32 v132, v56, v75
	ds_write_b32 v132, v164
	v_add_u32_e32 v130, v56, v76
	ds_write_b32 v130, v165
	v_add_u32_e32 v132, v56, v77
	ds_write_b32 v132, v166
	v_add_u32_e32 v130, v56, v78
	ds_write_b32 v130, v167
	v_add_u32_e32 v132, v56, v79
	ds_write_b32 v132, v168
	v_add_u32_e32 v130, v56, v80
	ds_write_b32 v130, v169
	v_add_u32_e32 v132, v56, v81
	ds_write_b32 v132, v170
	v_add_u32_e32 v130, v56, v82
	ds_write_b32 v130, v171
	v_add_u32_e32 v132, v56, v83
	ds_write_b32 v132, v172
	v_add_u32_e32 v130, v56, v84
	ds_write_b32 v130, v173
	v_add_u32_e32 v132, v56, v85
	ds_write_b32 v132, v174
	v_add_u32_e32 v130, v56, v86
	ds_write_b32 v130, v175
	v_add_u32_e32 v132, v56, v87
	ds_write_b32 v132, v176
	v_add_u32_e32 v130, v56, v88
	ds_write_b32 v130, v177
	v_add_u32_e32 v132, v56, v89
	ds_write_b32 v132, v178
	v_add_u32_e32 v130, v56, v90
	ds_write_b32 v130, v179
	v_add_u32_e32 v132, v56, v91
	ds_write_b32 v132, v180
	v_add_u32_e32 v130, v56, v92
	ds_write_b32 v130, v181
	v_add_u32_e32 v132, v56, v93
	ds_write_b32 v132, v182
	v_add_u32_e32 v130, v56, v94
	ds_write_b32 v130, v183
	v_add_u32_e32 v132, v56, v95
	ds_write_b32 v132, v184
	v_add_u32_e32 v130, v56, v96
	ds_write_b32 v130, v185
	v_add_u32_e32 v132, v56, v97
	ds_write_b32 v132, v186
	v_add_u32_e32 v130, v56, v98
	ds_write_b32 v130, v187
	s_waitcnt lgkmcnt(0)
	ds_read2_b32 v[136:137], v58 offset0:33 offset1:41
	ds_read2_b32 v[138:139], v58 offset1:8
	ds_read2_b32 v[140:141], v58 offset0:66 offset1:74
	ds_read2_b32 v[142:143], v58 offset0:99 offset1:107
	ds_read2_b32 v[144:145], v58 offset0:132 offset1:140
	ds_read2_b32 v[146:147], v58 offset0:165 offset1:173
	ds_read2_b32 v[148:149], v58 offset0:198 offset1:206
	ds_read2_b32 v[150:151], v58 offset0:231 offset1:239
	s_waitcnt lgkmcnt(6)
	v_cvt_pk_f16_f32 v130, v138, v136
	s_waitcnt lgkmcnt(4)
	v_cvt_pk_f16_f32 v131, v140, v142
	s_waitcnt lgkmcnt(2)
	v_cvt_pk_f16_f32 v132, v144, v146
	s_waitcnt lgkmcnt(0)
	v_cvt_pk_f16_f32 v133, v148, v150
	v_add_u32_e32 v136, s10, v59
	global_store_dwordx4 v[152:153], v[130:133], off
	v_add_u32_e32 v152, s10, v60
	v_ashrrev_i32_e32 v153, 31, v152
	v_cvt_pk_f16_f32 v130, v139, v137
	v_ashrrev_i32_e32 v137, 31, v136
	v_lshlrev_b64 v[136:137], 11, v[136:137]
	v_cvt_pk_f16_f32 v131, v141, v143
	v_cvt_pk_f16_f32 v132, v145, v147
	v_cvt_pk_f16_f32 v133, v149, v151
	v_lshl_add_u64 v[136:137], v[134:135], 0, v[136:137]
	global_store_dwordx4 v[136:137], v[130:133], off
	ds_read2_b32 v[136:137], v58 offset0:49 offset1:57
	ds_read2_b32 v[138:139], v58 offset0:16 offset1:24
	ds_read2_b32 v[140:141], v58 offset0:82 offset1:90
	ds_read2_b32 v[142:143], v58 offset0:115 offset1:123
	ds_read2_b32 v[144:145], v58 offset0:148 offset1:156
	ds_read2_b32 v[146:147], v58 offset0:181 offset1:189
	ds_read2_b32 v[148:149], v58 offset0:214 offset1:222
	ds_read2_b32 v[150:151], v58 offset0:247 offset1:255
	v_lshlrev_b64 v[152:153], 11, v[152:153]
	s_waitcnt lgkmcnt(6)
	v_cvt_pk_f16_f32 v130, v138, v136
	s_waitcnt lgkmcnt(4)
	v_cvt_pk_f16_f32 v131, v140, v142
	s_waitcnt lgkmcnt(2)
	v_cvt_pk_f16_f32 v132, v144, v146
	s_waitcnt lgkmcnt(0)
	v_cvt_pk_f16_f32 v133, v148, v150
	v_lshl_add_u64 v[152:153], v[134:135], 0, v[152:153]
	v_add_u32_e32 v136, s10, v61
	global_store_dwordx4 v[152:153], v[130:133], off
	s_nop 1
	v_cvt_pk_f16_f32 v130, v139, v137
	v_ashrrev_i32_e32 v137, 31, v136
	v_lshlrev_b64 v[136:137], 11, v[136:137]
	v_cvt_pk_f16_f32 v131, v141, v143
	v_cvt_pk_f16_f32 v132, v145, v147
	v_cvt_pk_f16_f32 v133, v149, v151
	v_lshl_add_u64 v[134:135], v[134:135], 0, v[136:137]
	global_store_dwordx4 v[134:135], v[130:133], off
	s_waitcnt lgkmcnt(0)
